# E27: K-loop load segments issue ds_reads first (DMA address math after), loop-end SALU moved into last MFMA block, on E20
# speedup vs baseline: 1.0004x; 1.0004x over previous
.LBB0_200:
	s_add_i32 s12, 0, 0x10000
	v_add_u32_e32 v2, s12, v188
	s_add_i32 s13, 0, 0x14000
	ds_read_b128 v[132:135], v2
	ds_read_b128 v[136:139], v2 offset:1024
	ds_read_b128 v[140:143], v2 offset:2048
	ds_read_b128 v[144:147], v2 offset:3072
	v_add_u32_e32 v2, s13, v188
	ds_read_b128 v[156:159], v2
	ds_read_b128 v[164:167], v2 offset:1024
	ds_read_b128 v[168:171], v2 offset:2048
	ds_read_b128 v[172:175], v2 offset:3072
	ds_read_b128 v[176:179], v189
	ds_read_b128 v[180:183], v189 offset:1024
	ds_read_b128 v[190:193], v189 offset:2048
	ds_read_b128 v[194:197], v189 offset:3072
	ds_read_b128 v[198:201], v189 offset:4096
	ds_read_b128 v[202:205], v189 offset:5120
	ds_read_b128 v[206:209], v189 offset:6144
	ds_read_b128 v[230:233], v189 offset:7168
	s_add_u32 s4, s0, 0xfffc0080
	s_addc_u32 s5, s1, -1
	s_cmp_eq_u32 s41, 12
	s_cselect_b32 s7, s20, s5
	s_cselect_b32 s6, s21, s4
	s_cselect_b32 s5, s22, s40
	s_cselect_b32 s4, s23, s37
	v_lshl_add_u64 v[160:161], s[0:1], 0, v[154:155]
	s_add_i32 m0, s85, 0xc000
	s_nop 0
	global_load_lds_dwordx4 v[160:161], off
	v_lshl_add_u64 v[160:161], s[0:1], 0, v[162:163]
	s_add_i32 m0, s85, 0xe000
	s_nop 0
	global_load_lds_dwordx4 v[160:161], off
	s_waitcnt vmcnt(8)
	s_waitcnt lgkmcnt(0)
	s_barrier
	s_setprio 1
	s_waitcnt lgkmcnt(0)
	v_mfma_f32_16x16x32_bf16 v[128:131], v[132:135], v[176:179], v[128:131]
	v_mfma_f32_16x16x32_bf16 v[124:127], v[140:143], v[176:179], v[124:127]
	v_mfma_f32_16x16x32_bf16 v[112:115], v[132:135], v[190:193], v[112:115]
	v_mfma_f32_16x16x32_bf16 v[108:111], v[140:143], v[190:193], v[108:111]
	v_mfma_f32_16x16x32_bf16 v[96:99], v[132:135], v[198:201], v[96:99]
	v_mfma_f32_16x16x32_bf16 v[92:95], v[140:143], v[198:201], v[92:95]
	v_mfma_f32_16x16x32_bf16 v[80:83], v[132:135], v[206:209], v[80:83]
	v_mfma_f32_16x16x32_bf16 v[76:79], v[140:143], v[206:209], v[76:79]
	v_mfma_f32_16x16x32_bf16 v[128:131], v[136:139], v[180:183], v[128:131]
	v_mfma_f32_16x16x32_bf16 v[124:127], v[144:147], v[180:183], v[124:127]
	v_mfma_f32_16x16x32_bf16 v[112:115], v[136:139], v[194:197], v[112:115]
	v_mfma_f32_16x16x32_bf16 v[108:111], v[144:147], v[194:197], v[108:111]
	v_mfma_f32_16x16x32_bf16 v[96:99], v[136:139], v[202:205], v[96:99]
	v_mfma_f32_16x16x32_bf16 v[92:95], v[144:147], v[202:205], v[92:95]
	v_mfma_f32_16x16x32_bf16 v[80:83], v[136:139], v[230:233], v[80:83]
	v_mfma_f32_16x16x32_bf16 v[76:79], v[144:147], v[230:233], v[76:79]
	s_setprio 0
	s_setprio 1
	v_mfma_f32_16x16x32_bf16 v[120:123], v[156:159], v[176:179], v[120:123]
	v_mfma_f32_16x16x32_bf16 v[116:119], v[168:171], v[176:179], v[116:119]
	v_mfma_f32_16x16x32_bf16 v[104:107], v[156:159], v[190:193], v[104:107]
	v_mfma_f32_16x16x32_bf16 v[100:103], v[168:171], v[190:193], v[100:103]
	v_mfma_f32_16x16x32_bf16 v[88:91], v[156:159], v[198:201], v[88:91]
	v_mfma_f32_16x16x32_bf16 v[84:87], v[168:171], v[198:201], v[84:87]
	v_mfma_f32_16x16x32_bf16 v[72:75], v[156:159], v[206:209], v[72:75]
	v_mfma_f32_16x16x32_bf16 v[68:71], v[168:171], v[206:209], v[68:71]
	v_mfma_f32_16x16x32_bf16 v[120:123], v[164:167], v[180:183], v[120:123]
	v_mfma_f32_16x16x32_bf16 v[116:119], v[172:175], v[180:183], v[116:119]
	v_mfma_f32_16x16x32_bf16 v[104:107], v[164:167], v[194:197], v[104:107]
	v_mfma_f32_16x16x32_bf16 v[100:103], v[172:175], v[194:197], v[100:103]
	v_mfma_f32_16x16x32_bf16 v[88:91], v[164:167], v[202:205], v[88:91]
	v_mfma_f32_16x16x32_bf16 v[84:87], v[172:175], v[202:205], v[84:87]
	v_mfma_f32_16x16x32_bf16 v[72:75], v[164:167], v[230:233], v[72:75]
	v_mfma_f32_16x16x32_bf16 v[68:71], v[172:175], v[230:233], v[68:71]
	s_setprio 0
	s_barrier
	ds_read_b128 v[176:179], v189 offset:16384
	ds_read_b128 v[180:183], v189 offset:17408
	ds_read_b128 v[190:193], v189 offset:18432
	ds_read_b128 v[194:197], v189 offset:19456
	ds_read_b128 v[198:201], v189 offset:20480
	ds_read_b128 v[202:205], v189 offset:21504
	ds_read_b128 v[206:209], v189 offset:22528
	ds_read_b128 v[230:233], v189 offset:23552
	s_add_i32 s12, s12, s24
	v_lshl_add_u64 v[160:161], s[4:5], 0, v[148:149]
	s_mov_b32 m0, s12
	s_nop 0
	global_load_lds_dwordx4 v[160:161], off
	s_add_i32 m0, s12, 0x2000
	s_add_u32 vcc_lo, s4, 0x10000
	v_lshl_add_u64 v[184:185], s[4:5], 0, v[152:153]
	s_addc_u32 vcc_hi, s5, 0
	s_add_i32 s12, s13, s24
	global_load_lds_dwordx4 v[184:185], off
	v_lshl_add_u64 v[234:235], vcc, 0, v[148:149]
	s_mov_b32 m0, s12
	v_lshl_add_u64 v[240:241], s[6:7], 0, v[150:151]
	global_load_lds_dwordx4 v[234:235], off
	v_lshl_add_u64 v[234:235], vcc, 0, v[152:153]
	s_add_i32 m0, s12, 0x2000
	s_nop 0
	global_load_lds_dwordx4 v[234:235], off
	v_lshl_add_u64 v[234:235], s[6:7], 0, v[0:1]
	s_mov_b32 m0, s85
	s_nop 0
	global_load_lds_dwordx4 v[234:235], off
	s_mov_b32 m0, s87
	s_nop 0
	global_load_lds_dwordx4 v[240:241], off
	s_waitcnt vmcnt(8)
	s_waitcnt lgkmcnt(0)
	s_barrier
	s_setprio 1
	s_waitcnt lgkmcnt(0)
	v_mfma_f32_16x16x32_bf16 v[64:67], v[132:135], v[176:179], v[64:67]
	v_mfma_f32_16x16x32_bf16 v[60:63], v[140:143], v[176:179], v[60:63]
	v_mfma_f32_16x16x32_bf16 v[48:51], v[132:135], v[190:193], v[48:51]
	v_mfma_f32_16x16x32_bf16 v[44:47], v[140:143], v[190:193], v[44:47]
	v_mfma_f32_16x16x32_bf16 v[32:35], v[132:135], v[198:201], v[32:35]
	v_mfma_f32_16x16x32_bf16 v[28:31], v[140:143], v[198:201], v[28:31]
	v_mfma_f32_16x16x32_bf16 v[16:19], v[132:135], v[206:209], v[16:19]
	v_mfma_f32_16x16x32_bf16 v[12:15], v[140:143], v[206:209], v[12:15]
	v_mfma_f32_16x16x32_bf16 v[64:67], v[136:139], v[180:183], v[64:67]
	v_mfma_f32_16x16x32_bf16 v[60:63], v[144:147], v[180:183], v[60:63]
	v_mfma_f32_16x16x32_bf16 v[48:51], v[136:139], v[194:197], v[48:51]
	v_mfma_f32_16x16x32_bf16 v[44:47], v[144:147], v[194:197], v[44:47]
	v_mfma_f32_16x16x32_bf16 v[32:35], v[136:139], v[202:205], v[32:35]
	v_mfma_f32_16x16x32_bf16 v[28:31], v[144:147], v[202:205], v[28:31]
	v_mfma_f32_16x16x32_bf16 v[16:19], v[136:139], v[230:233], v[16:19]
	v_mfma_f32_16x16x32_bf16 v[12:15], v[144:147], v[230:233], v[12:15]
	s_setprio 0
	s_setprio 1
	v_mfma_f32_16x16x32_bf16 v[56:59], v[156:159], v[176:179], v[56:59]
	v_mfma_f32_16x16x32_bf16 v[52:55], v[168:171], v[176:179], v[52:55]
	v_mfma_f32_16x16x32_bf16 v[40:43], v[156:159], v[190:193], v[40:43]
	v_mfma_f32_16x16x32_bf16 v[36:39], v[168:171], v[190:193], v[36:39]
	v_mfma_f32_16x16x32_bf16 v[24:27], v[156:159], v[198:201], v[24:27]
	v_mfma_f32_16x16x32_bf16 v[20:23], v[168:171], v[198:201], v[20:23]
	v_mfma_f32_16x16x32_bf16 v[8:11], v[156:159], v[206:209], v[8:11]
	v_mfma_f32_16x16x32_bf16 v[4:7], v[168:171], v[206:209], v[4:7]
	v_mfma_f32_16x16x32_bf16 v[56:59], v[164:167], v[180:183], v[56:59]
	v_mfma_f32_16x16x32_bf16 v[52:55], v[172:175], v[180:183], v[52:55]
	v_mfma_f32_16x16x32_bf16 v[40:43], v[164:167], v[194:197], v[40:43]
	v_mfma_f32_16x16x32_bf16 v[36:39], v[172:175], v[194:197], v[36:39]
	v_mfma_f32_16x16x32_bf16 v[24:27], v[164:167], v[202:205], v[24:27]
	v_mfma_f32_16x16x32_bf16 v[20:23], v[172:175], v[202:205], v[20:23]
	v_mfma_f32_16x16x32_bf16 v[8:11], v[164:167], v[230:233], v[8:11]
	v_mfma_f32_16x16x32_bf16 v[4:7], v[172:175], v[230:233], v[4:7]
	s_setprio 0
	s_barrier
	s_add_i32 s12, 0, 0x18000
	v_add_u32_e32 v2, s12, v188
	s_add_i32 s13, 0, 0x1c000
	ds_read_b128 v[132:135], v2
	ds_read_b128 v[136:139], v2 offset:1024
	ds_read_b128 v[140:143], v2 offset:2048
	ds_read_b128 v[144:147], v2 offset:3072
	v_add_u32_e32 v2, s13, v188
	ds_read_b128 v[156:159], v2
	ds_read_b128 v[164:167], v2 offset:1024
	ds_read_b128 v[168:171], v2 offset:2048
	ds_read_b128 v[172:175], v2 offset:3072
	ds_read_b128 v[176:179], v189 offset:32768
	ds_read_b128 v[180:183], v189 offset:33792
	ds_read_b128 v[190:193], v189 offset:34816
	ds_read_b128 v[194:197], v189 offset:35840
	ds_read_b128 v[198:201], v189 offset:36864
	ds_read_b128 v[202:205], v189 offset:37888
	ds_read_b128 v[206:209], v189 offset:38912
	ds_read_b128 v[230:233], v189 offset:39936
	s_add_u32 s6, s6, 0x40000
	s_addc_u32 s7, s7, 0
	s_mov_b32 m0, s88
	v_lshl_add_u64 v[242:243], s[6:7], 0, v[0:1]
	global_load_lds_dwordx4 v[242:243], off
	v_lshl_add_u64 v[242:243], s[6:7], 0, v[150:151]
	s_mov_b32 m0, s89
	s_nop 0
	global_load_lds_dwordx4 v[242:243], off
	s_waitcnt vmcnt(8)
	s_waitcnt lgkmcnt(0)
	s_barrier
	s_setprio 1
	s_waitcnt lgkmcnt(0)
	v_mfma_f32_16x16x32_bf16 v[128:131], v[132:135], v[176:179], v[128:131]
	v_mfma_f32_16x16x32_bf16 v[124:127], v[140:143], v[176:179], v[124:127]
	v_mfma_f32_16x16x32_bf16 v[112:115], v[132:135], v[190:193], v[112:115]
	v_mfma_f32_16x16x32_bf16 v[108:111], v[140:143], v[190:193], v[108:111]
	v_mfma_f32_16x16x32_bf16 v[96:99], v[132:135], v[198:201], v[96:99]
	v_mfma_f32_16x16x32_bf16 v[92:95], v[140:143], v[198:201], v[92:95]
	v_mfma_f32_16x16x32_bf16 v[80:83], v[132:135], v[206:209], v[80:83]
	v_mfma_f32_16x16x32_bf16 v[76:79], v[140:143], v[206:209], v[76:79]
	v_mfma_f32_16x16x32_bf16 v[128:131], v[136:139], v[180:183], v[128:131]
	v_mfma_f32_16x16x32_bf16 v[124:127], v[144:147], v[180:183], v[124:127]
	v_mfma_f32_16x16x32_bf16 v[112:115], v[136:139], v[194:197], v[112:115]
	v_mfma_f32_16x16x32_bf16 v[108:111], v[144:147], v[194:197], v[108:111]
	v_mfma_f32_16x16x32_bf16 v[96:99], v[136:139], v[202:205], v[96:99]
	v_mfma_f32_16x16x32_bf16 v[92:95], v[144:147], v[202:205], v[92:95]
	v_mfma_f32_16x16x32_bf16 v[80:83], v[136:139], v[230:233], v[80:83]
	v_mfma_f32_16x16x32_bf16 v[76:79], v[144:147], v[230:233], v[76:79]
	s_setprio 0
	s_setprio 1
	v_mfma_f32_16x16x32_bf16 v[120:123], v[156:159], v[176:179], v[120:123]
	v_mfma_f32_16x16x32_bf16 v[116:119], v[168:171], v[176:179], v[116:119]
	v_mfma_f32_16x16x32_bf16 v[104:107], v[156:159], v[190:193], v[104:107]
	v_mfma_f32_16x16x32_bf16 v[100:103], v[168:171], v[190:193], v[100:103]
	v_mfma_f32_16x16x32_bf16 v[88:91], v[156:159], v[198:201], v[88:91]
	v_mfma_f32_16x16x32_bf16 v[84:87], v[168:171], v[198:201], v[84:87]
	v_mfma_f32_16x16x32_bf16 v[72:75], v[156:159], v[206:209], v[72:75]
	v_mfma_f32_16x16x32_bf16 v[68:71], v[168:171], v[206:209], v[68:71]
	v_mfma_f32_16x16x32_bf16 v[120:123], v[164:167], v[180:183], v[120:123]
	v_mfma_f32_16x16x32_bf16 v[116:119], v[172:175], v[180:183], v[116:119]
	v_mfma_f32_16x16x32_bf16 v[104:107], v[164:167], v[194:197], v[104:107]
	v_mfma_f32_16x16x32_bf16 v[100:103], v[172:175], v[194:197], v[100:103]
	v_mfma_f32_16x16x32_bf16 v[88:91], v[164:167], v[202:205], v[88:91]
	v_mfma_f32_16x16x32_bf16 v[84:87], v[172:175], v[202:205], v[84:87]
	v_mfma_f32_16x16x32_bf16 v[72:75], v[164:167], v[230:233], v[72:75]
	v_mfma_f32_16x16x32_bf16 v[68:71], v[172:175], v[230:233], v[68:71]
	s_setprio 0
	s_barrier
	ds_read_b128 v[176:179], v189 offset:49152
	ds_read_b128 v[180:183], v189 offset:50176
	ds_read_b128 v[190:193], v189 offset:51200
	ds_read_b128 v[194:197], v189 offset:52224
	ds_read_b128 v[198:201], v189 offset:53248
	ds_read_b128 v[202:205], v189 offset:54272
	ds_read_b128 v[206:209], v189 offset:55296
	ds_read_b128 v[230:233], v189 offset:56320
	s_add_i32 s6, s12, s24
	v_lshl_add_u64 v[160:161], v[160:161], 0, s[26:27]
	s_mov_b32 m0, s6
	s_nop 0
	global_load_lds_dwordx4 v[160:161], off
	s_add_i32 m0, s6, 0x2000
	s_add_u32 s4, s4, 0x10080
	v_lshl_add_u64 v[160:161], v[184:185], 0, s[26:27]
	s_addc_u32 s5, s5, 0
	s_add_i32 s6, s13, s24
	global_load_lds_dwordx4 v[160:161], off
	v_lshl_add_u64 v[160:161], s[4:5], 0, v[148:149]
	s_mov_b32 m0, s6
	s_nop 0
	global_load_lds_dwordx4 v[160:161], off
	v_lshl_add_u64 v[160:161], s[4:5], 0, v[152:153]
	s_add_i32 m0, s6, 0x2000
	s_nop 0
	global_load_lds_dwordx4 v[160:161], off
	v_lshl_add_u64 v[160:161], v[234:235], 0, s[26:27]
	s_mov_b32 m0, s91
	s_nop 0
	global_load_lds_dwordx4 v[160:161], off
	v_lshl_add_u64 v[160:161], v[240:241], 0, s[26:27]
	s_mov_b32 m0, s92
	s_nop 0
	global_load_lds_dwordx4 v[160:161], off
	s_waitcnt vmcnt(8)
	s_waitcnt lgkmcnt(0)
	s_barrier
	s_setprio 1
	s_waitcnt lgkmcnt(0)
	v_mfma_f32_16x16x32_bf16 v[64:67], v[132:135], v[176:179], v[64:67]
	v_mfma_f32_16x16x32_bf16 v[60:63], v[140:143], v[176:179], v[60:63]
	v_mfma_f32_16x16x32_bf16 v[48:51], v[132:135], v[190:193], v[48:51]
	v_mfma_f32_16x16x32_bf16 v[44:47], v[140:143], v[190:193], v[44:47]
	v_mfma_f32_16x16x32_bf16 v[32:35], v[132:135], v[198:201], v[32:35]
	v_mfma_f32_16x16x32_bf16 v[28:31], v[140:143], v[198:201], v[28:31]
	v_mfma_f32_16x16x32_bf16 v[16:19], v[132:135], v[206:209], v[16:19]
	v_mfma_f32_16x16x32_bf16 v[12:15], v[140:143], v[206:209], v[12:15]
	v_mfma_f32_16x16x32_bf16 v[64:67], v[136:139], v[180:183], v[64:67]
	v_mfma_f32_16x16x32_bf16 v[60:63], v[144:147], v[180:183], v[60:63]
	v_mfma_f32_16x16x32_bf16 v[48:51], v[136:139], v[194:197], v[48:51]
	v_mfma_f32_16x16x32_bf16 v[44:47], v[144:147], v[194:197], v[44:47]
	v_mfma_f32_16x16x32_bf16 v[32:35], v[136:139], v[202:205], v[32:35]
	v_mfma_f32_16x16x32_bf16 v[28:31], v[144:147], v[202:205], v[28:31]
	v_mfma_f32_16x16x32_bf16 v[16:19], v[136:139], v[230:233], v[16:19]
	v_mfma_f32_16x16x32_bf16 v[12:15], v[144:147], v[230:233], v[12:15]
	s_setprio 0
	s_setprio 1
	v_mfma_f32_16x16x32_bf16 v[56:59], v[156:159], v[176:179], v[56:59]
	v_mfma_f32_16x16x32_bf16 v[52:55], v[168:171], v[176:179], v[52:55]
	v_mfma_f32_16x16x32_bf16 v[40:43], v[156:159], v[190:193], v[40:43]
	v_mfma_f32_16x16x32_bf16 v[36:39], v[168:171], v[190:193], v[36:39]
	v_mfma_f32_16x16x32_bf16 v[24:27], v[156:159], v[198:201], v[24:27]
	v_mfma_f32_16x16x32_bf16 v[20:23], v[168:171], v[198:201], v[20:23]
	v_mfma_f32_16x16x32_bf16 v[8:11], v[156:159], v[206:209], v[8:11]
	v_mfma_f32_16x16x32_bf16 v[4:7], v[168:171], v[206:209], v[4:7]
	s_add_i32 s41, s41, 2
	s_add_u32 s0, s0, 0x100
	s_addc_u32 s1, s1, 0
	s_add_u32 s37, s37, 0x100
	s_addc_u32 s40, s40, 0
	s_cmp_gt_u32 s41, 13
	v_mfma_f32_16x16x32_bf16 v[56:59], v[164:167], v[180:183], v[56:59]
	v_mfma_f32_16x16x32_bf16 v[52:55], v[172:175], v[180:183], v[52:55]
	v_mfma_f32_16x16x32_bf16 v[40:43], v[164:167], v[194:197], v[40:43]
	v_mfma_f32_16x16x32_bf16 v[36:39], v[172:175], v[194:197], v[36:39]
	v_mfma_f32_16x16x32_bf16 v[24:27], v[164:167], v[202:205], v[24:27]
	v_mfma_f32_16x16x32_bf16 v[20:23], v[172:175], v[202:205], v[20:23]
	v_mfma_f32_16x16x32_bf16 v[8:11], v[164:167], v[230:233], v[8:11]
	v_mfma_f32_16x16x32_bf16 v[4:7], v[172:175], v[230:233], v[4:7]
	s_setprio 0
	s_barrier
	s_cbranch_scc0 .LBB0_200
	s_mov_b64 s[26:27], 0x80
	s_and_b64 vcc, exec, s[66:67]
	s_cbranch_vccz .LBB0_203
	s_barrier

.LBB0_1564:
	s_add_u32 s42, s26, s34
	s_addc_u32 s43, s27, s35
	s_add_u32 s40, s42, 0x100
	s_addc_u32 s41, s43, 0
	s_and_b64 s[38:39], s[30:31], exec
	s_cselect_b32 s39, s17, s41
	s_cselect_b32 s38, s63, s40
	s_add_u32 s34, s24, s34
	s_addc_u32 s35, s25, s35
	s_add_u32 s34, s34, 0x100
	s_addc_u32 s35, s35, 0
	s_add_i32 s73, 0, 0x10000
	s_and_b64 s[30:31], s[30:31], exec
	s_cselect_b32 s41, s15, s35
	s_cselect_b32 s40, s64, s34
	s_add_i32 s31, 0, 0x14000
	v_add_u32_e32 v142, s73, v145
	ds_read_b128 v[138:141], v142
	ds_read_b128 v[148:151], v142 offset:1024
	ds_read_b128 v[152:155], v142 offset:2048
	ds_read_b128 v[156:159], v142 offset:3072
	v_add_u32_e32 v142, s31, v145
	ds_read_b128 v[160:163], v142
	ds_read_b128 v[164:167], v142 offset:1024
	ds_read_b128 v[168:171], v142 offset:2048
	ds_read_b128 v[172:175], v142 offset:3072
	ds_read_b128 v[176:179], v146
	ds_read_b128 v[180:183], v146 offset:1024
	ds_read_b128 v[184:187], v146 offset:2048
	ds_read_b128 v[188:191], v146 offset:3072
	ds_read_b128 v[192:195], v146 offset:4096
	ds_read_b128 v[196:199], v146 offset:5120
	ds_read_b128 v[200:203], v146 offset:6144
	ds_read_b128 v[204:207], v146 offset:7168
	s_add_u32 s44, s42, 0x10080
	s_addc_u32 s45, s43, 0
	s_add_i32 s72, s73, s52
	s_add_i32 m0, s53, 0xc000
	s_add_i32 s75, s53, 0xe000
	s_add_i32 s69, s72, 0x2000
	s_add_u32 s42, s40, 0x10000
	s_addc_u32 s43, s41, 0
	s_add_i32 s71, s31, s52
	s_add_i32 s70, s71, 0x2000
	s_add_i32 s68, 0, 0x18000
	s_add_i32 s67, 0, 0x1c000
	s_add_u32 s34, s38, 0x10000
	s_addc_u32 s35, s39, 0
	s_add_i32 s66, s68, s52
	s_add_i32 s65, s66, 0x2000
	s_add_u32 s30, s40, 0x10080
	s_addc_u32 s31, s41, 0
	s_add_i32 s74, s67, s52
	s_add_i32 s73, s74, 0x2000
	v_lshl_add_u64 v[142:143], s[44:45], 0, v[136:137]
	global_load_lds_dwordx4 v[142:143], off
	v_lshl_add_u64 v[142:143], s[44:45], 0, v[132:133]
	s_mov_b32 m0, s75
	s_nop 0
	global_load_lds_dwordx4 v[142:143], off
	s_waitcnt vmcnt(8)
	s_waitcnt lgkmcnt(0)
	s_barrier
	s_setprio 1
	s_waitcnt lgkmcnt(0)
	v_mfma_f32_16x16x32_bf16 v[128:131], v[138:141], v[176:179], v[128:131]
	v_mfma_f32_16x16x32_bf16 v[124:127], v[152:155], v[176:179], v[124:127]
	v_mfma_f32_16x16x32_bf16 v[112:115], v[138:141], v[184:187], v[112:115]
	v_mfma_f32_16x16x32_bf16 v[108:111], v[152:155], v[184:187], v[108:111]
	v_mfma_f32_16x16x32_bf16 v[96:99], v[138:141], v[192:195], v[96:99]
	v_mfma_f32_16x16x32_bf16 v[92:95], v[152:155], v[192:195], v[92:95]
	v_mfma_f32_16x16x32_bf16 v[80:83], v[138:141], v[200:203], v[80:83]
	v_mfma_f32_16x16x32_bf16 v[76:79], v[152:155], v[200:203], v[76:79]
	v_mfma_f32_16x16x32_bf16 v[128:131], v[148:151], v[180:183], v[128:131]
	v_mfma_f32_16x16x32_bf16 v[124:127], v[156:159], v[180:183], v[124:127]
	v_mfma_f32_16x16x32_bf16 v[112:115], v[148:151], v[188:191], v[112:115]
	v_mfma_f32_16x16x32_bf16 v[108:111], v[156:159], v[188:191], v[108:111]
	v_mfma_f32_16x16x32_bf16 v[96:99], v[148:151], v[196:199], v[96:99]
	v_mfma_f32_16x16x32_bf16 v[92:95], v[156:159], v[196:199], v[92:95]
	v_mfma_f32_16x16x32_bf16 v[80:83], v[148:151], v[204:207], v[80:83]
	v_mfma_f32_16x16x32_bf16 v[76:79], v[156:159], v[204:207], v[76:79]
	s_setprio 0
	s_setprio 1
	v_mfma_f32_16x16x32_bf16 v[120:123], v[160:163], v[176:179], v[120:123]
	v_mfma_f32_16x16x32_bf16 v[116:119], v[168:171], v[176:179], v[116:119]
	v_mfma_f32_16x16x32_bf16 v[104:107], v[160:163], v[184:187], v[104:107]
	v_mfma_f32_16x16x32_bf16 v[100:103], v[168:171], v[184:187], v[100:103]
	v_mfma_f32_16x16x32_bf16 v[88:91], v[160:163], v[192:195], v[88:91]
	v_mfma_f32_16x16x32_bf16 v[84:87], v[168:171], v[192:195], v[84:87]
	v_mfma_f32_16x16x32_bf16 v[72:75], v[160:163], v[200:203], v[72:75]
	v_mfma_f32_16x16x32_bf16 v[68:71], v[168:171], v[200:203], v[68:71]
	v_mfma_f32_16x16x32_bf16 v[120:123], v[164:167], v[180:183], v[120:123]
	v_mfma_f32_16x16x32_bf16 v[116:119], v[172:175], v[180:183], v[116:119]
	v_mfma_f32_16x16x32_bf16 v[104:107], v[164:167], v[188:191], v[104:107]
	v_mfma_f32_16x16x32_bf16 v[100:103], v[172:175], v[188:191], v[100:103]
	v_mfma_f32_16x16x32_bf16 v[88:91], v[164:167], v[196:199], v[88:91]
	v_mfma_f32_16x16x32_bf16 v[84:87], v[172:175], v[196:199], v[84:87]
	v_mfma_f32_16x16x32_bf16 v[72:75], v[164:167], v[204:207], v[72:75]
	v_mfma_f32_16x16x32_bf16 v[68:71], v[172:175], v[204:207], v[68:71]
	s_setprio 0
	s_barrier
	ds_read_b128 v[176:179], v146 offset:16384
	ds_read_b128 v[180:183], v146 offset:17408
	ds_read_b128 v[184:187], v146 offset:18432
	ds_read_b128 v[188:191], v146 offset:19456
	ds_read_b128 v[192:195], v146 offset:20480
	ds_read_b128 v[196:199], v146 offset:21504
	ds_read_b128 v[200:203], v146 offset:22528
	ds_read_b128 v[204:207], v146 offset:23552
	s_mov_b32 m0, s72
	v_lshl_add_u64 v[142:143], s[40:41], 0, v[134:135]
	global_load_lds_dwordx4 v[142:143], off
	v_lshl_add_u64 v[208:209], s[40:41], 0, v[0:1]
	s_mov_b32 m0, s69
	v_lshl_add_u64 v[230:231], s[42:43], 0, v[134:135]
	global_load_lds_dwordx4 v[208:209], off
	s_mov_b32 m0, s71
	v_lshl_add_u64 v[232:233], s[38:39], 0, v[132:133]
	global_load_lds_dwordx4 v[230:231], off
	v_lshl_add_u64 v[230:231], s[42:43], 0, v[0:1]
	s_mov_b32 m0, s70
	s_nop 0
	global_load_lds_dwordx4 v[230:231], off
	v_lshl_add_u64 v[230:231], s[38:39], 0, v[136:137]
	s_mov_b32 m0, s53
	s_nop 0
	global_load_lds_dwordx4 v[230:231], off
	s_mov_b32 m0, s54
	s_nop 0
	global_load_lds_dwordx4 v[232:233], off
	s_waitcnt vmcnt(8)
	s_waitcnt lgkmcnt(0)
	s_barrier
	s_setprio 1
	s_waitcnt lgkmcnt(0)
	v_mfma_f32_16x16x32_bf16 v[64:67], v[138:141], v[176:179], v[64:67]
	v_mfma_f32_16x16x32_bf16 v[60:63], v[152:155], v[176:179], v[60:63]
	v_mfma_f32_16x16x32_bf16 v[48:51], v[138:141], v[184:187], v[48:51]
	v_mfma_f32_16x16x32_bf16 v[44:47], v[152:155], v[184:187], v[44:47]
	v_mfma_f32_16x16x32_bf16 v[32:35], v[138:141], v[192:195], v[32:35]
	v_mfma_f32_16x16x32_bf16 v[28:31], v[152:155], v[192:195], v[28:31]
	v_mfma_f32_16x16x32_bf16 v[20:23], v[138:141], v[200:203], v[20:23]
	v_mfma_f32_16x16x32_bf16 v[12:15], v[152:155], v[200:203], v[12:15]
	v_mfma_f32_16x16x32_bf16 v[64:67], v[148:151], v[180:183], v[64:67]
	v_mfma_f32_16x16x32_bf16 v[60:63], v[156:159], v[180:183], v[60:63]
	v_mfma_f32_16x16x32_bf16 v[48:51], v[148:151], v[188:191], v[48:51]
	v_mfma_f32_16x16x32_bf16 v[44:47], v[156:159], v[188:191], v[44:47]
	v_mfma_f32_16x16x32_bf16 v[32:35], v[148:151], v[196:199], v[32:35]
	v_mfma_f32_16x16x32_bf16 v[28:31], v[156:159], v[196:199], v[28:31]
	v_mfma_f32_16x16x32_bf16 v[20:23], v[148:151], v[204:207], v[20:23]
	v_mfma_f32_16x16x32_bf16 v[12:15], v[156:159], v[204:207], v[12:15]
	s_setprio 0
	s_setprio 1
	v_mfma_f32_16x16x32_bf16 v[56:59], v[160:163], v[176:179], v[56:59]
	v_mfma_f32_16x16x32_bf16 v[52:55], v[168:171], v[176:179], v[52:55]
	v_mfma_f32_16x16x32_bf16 v[40:43], v[160:163], v[184:187], v[40:43]
	v_mfma_f32_16x16x32_bf16 v[36:39], v[168:171], v[184:187], v[36:39]
	v_mfma_f32_16x16x32_bf16 v[24:27], v[160:163], v[192:195], v[24:27]
	v_mfma_f32_16x16x32_bf16 v[16:19], v[168:171], v[192:195], v[16:19]
	v_mfma_f32_16x16x32_bf16 v[8:11], v[160:163], v[200:203], v[8:11]
	v_mfma_f32_16x16x32_bf16 v[4:7], v[168:171], v[200:203], v[4:7]
	v_mfma_f32_16x16x32_bf16 v[56:59], v[164:167], v[180:183], v[56:59]
	v_mfma_f32_16x16x32_bf16 v[52:55], v[172:175], v[180:183], v[52:55]
	v_mfma_f32_16x16x32_bf16 v[40:43], v[164:167], v[188:191], v[40:43]
	v_mfma_f32_16x16x32_bf16 v[36:39], v[172:175], v[188:191], v[36:39]
	v_mfma_f32_16x16x32_bf16 v[24:27], v[164:167], v[196:199], v[24:27]
	v_mfma_f32_16x16x32_bf16 v[16:19], v[172:175], v[196:199], v[16:19]
	v_mfma_f32_16x16x32_bf16 v[8:11], v[164:167], v[204:207], v[8:11]
	v_mfma_f32_16x16x32_bf16 v[4:7], v[172:175], v[204:207], v[4:7]
	s_setprio 0
	s_barrier
	v_add_u32_e32 v147, s68, v145
	ds_read_b128 v[138:141], v147
	ds_read_b128 v[148:151], v147 offset:1024
	ds_read_b128 v[152:155], v147 offset:2048
	ds_read_b128 v[156:159], v147 offset:3072
	v_add_u32_e32 v147, s67, v145
	ds_read_b128 v[160:163], v147
	ds_read_b128 v[164:167], v147 offset:1024
	ds_read_b128 v[168:171], v147 offset:2048
	ds_read_b128 v[172:175], v147 offset:3072
	ds_read_b128 v[176:179], v146 offset:32768
	ds_read_b128 v[180:183], v146 offset:33792
	ds_read_b128 v[184:187], v146 offset:34816
	ds_read_b128 v[188:191], v146 offset:35840
	ds_read_b128 v[192:195], v146 offset:36864
	ds_read_b128 v[196:199], v146 offset:37888
	ds_read_b128 v[200:203], v146 offset:38912
	ds_read_b128 v[204:207], v146 offset:39936
	s_mov_b32 m0, s55
	v_lshl_add_u64 v[234:235], s[34:35], 0, v[136:137]
	global_load_lds_dwordx4 v[234:235], off
	v_lshl_add_u64 v[234:235], s[34:35], 0, v[132:133]
	s_mov_b32 m0, s56
	s_nop 0
	global_load_lds_dwordx4 v[234:235], off
	s_waitcnt vmcnt(8)
	s_waitcnt lgkmcnt(0)
	s_barrier
	s_setprio 1
	s_waitcnt lgkmcnt(0)
	v_mfma_f32_16x16x32_bf16 v[128:131], v[138:141], v[176:179], v[128:131]
	v_mfma_f32_16x16x32_bf16 v[124:127], v[152:155], v[176:179], v[124:127]
	v_mfma_f32_16x16x32_bf16 v[112:115], v[138:141], v[184:187], v[112:115]
	v_mfma_f32_16x16x32_bf16 v[108:111], v[152:155], v[184:187], v[108:111]
	v_mfma_f32_16x16x32_bf16 v[96:99], v[138:141], v[192:195], v[96:99]
	v_mfma_f32_16x16x32_bf16 v[92:95], v[152:155], v[192:195], v[92:95]
	v_mfma_f32_16x16x32_bf16 v[80:83], v[138:141], v[200:203], v[80:83]
	v_mfma_f32_16x16x32_bf16 v[76:79], v[152:155], v[200:203], v[76:79]
	v_mfma_f32_16x16x32_bf16 v[128:131], v[148:151], v[180:183], v[128:131]
	v_mfma_f32_16x16x32_bf16 v[124:127], v[156:159], v[180:183], v[124:127]
	v_mfma_f32_16x16x32_bf16 v[112:115], v[148:151], v[188:191], v[112:115]
	v_mfma_f32_16x16x32_bf16 v[108:111], v[156:159], v[188:191], v[108:111]
	v_mfma_f32_16x16x32_bf16 v[96:99], v[148:151], v[196:199], v[96:99]
	v_mfma_f32_16x16x32_bf16 v[92:95], v[156:159], v[196:199], v[92:95]
	v_mfma_f32_16x16x32_bf16 v[80:83], v[148:151], v[204:207], v[80:83]
	v_mfma_f32_16x16x32_bf16 v[76:79], v[156:159], v[204:207], v[76:79]
	s_setprio 0
	s_setprio 1
	v_mfma_f32_16x16x32_bf16 v[120:123], v[160:163], v[176:179], v[120:123]
	v_mfma_f32_16x16x32_bf16 v[116:119], v[168:171], v[176:179], v[116:119]
	v_mfma_f32_16x16x32_bf16 v[104:107], v[160:163], v[184:187], v[104:107]
	v_mfma_f32_16x16x32_bf16 v[100:103], v[168:171], v[184:187], v[100:103]
	v_mfma_f32_16x16x32_bf16 v[88:91], v[160:163], v[192:195], v[88:91]
	v_mfma_f32_16x16x32_bf16 v[84:87], v[168:171], v[192:195], v[84:87]
	v_mfma_f32_16x16x32_bf16 v[72:75], v[160:163], v[200:203], v[72:75]
	v_mfma_f32_16x16x32_bf16 v[68:71], v[168:171], v[200:203], v[68:71]
	v_mfma_f32_16x16x32_bf16 v[120:123], v[164:167], v[180:183], v[120:123]
	v_mfma_f32_16x16x32_bf16 v[116:119], v[172:175], v[180:183], v[116:119]
	v_mfma_f32_16x16x32_bf16 v[104:107], v[164:167], v[188:191], v[104:107]
	v_mfma_f32_16x16x32_bf16 v[100:103], v[172:175], v[188:191], v[100:103]
	v_mfma_f32_16x16x32_bf16 v[88:91], v[164:167], v[196:199], v[88:91]
	v_mfma_f32_16x16x32_bf16 v[84:87], v[172:175], v[196:199], v[84:87]
	v_mfma_f32_16x16x32_bf16 v[72:75], v[164:167], v[204:207], v[72:75]
	v_mfma_f32_16x16x32_bf16 v[68:71], v[172:175], v[204:207], v[68:71]
	s_setprio 0
	s_barrier
	ds_read_b128 v[176:179], v146 offset:49152
	ds_read_b128 v[180:183], v146 offset:50176
	ds_read_b128 v[184:187], v146 offset:51200
	ds_read_b128 v[188:191], v146 offset:52224
	ds_read_b128 v[192:195], v146 offset:53248
	ds_read_b128 v[196:199], v146 offset:54272
	ds_read_b128 v[200:203], v146 offset:55296
	ds_read_b128 v[204:207], v146 offset:56320
	s_mov_b32 m0, s66
	v_lshl_add_u64 v[142:143], v[142:143], 0, s[76:77]
	global_load_lds_dwordx4 v[142:143], off
	v_lshl_add_u64 v[142:143], v[208:209], 0, s[76:77]
	s_mov_b32 m0, s65
	s_nop 0
	global_load_lds_dwordx4 v[142:143], off
	v_lshl_add_u64 v[142:143], s[30:31], 0, v[134:135]
	s_mov_b32 m0, s74
	s_nop 0
	global_load_lds_dwordx4 v[142:143], off
	v_lshl_add_u64 v[142:143], s[30:31], 0, v[0:1]
	s_mov_b32 m0, s73
	s_nop 0
	global_load_lds_dwordx4 v[142:143], off
	v_lshl_add_u64 v[142:143], v[230:231], 0, s[76:77]
	s_mov_b32 m0, s59
	s_nop 0
	global_load_lds_dwordx4 v[142:143], off
	v_lshl_add_u64 v[142:143], v[232:233], 0, s[76:77]
	s_mov_b32 m0, s60
	s_nop 0
	global_load_lds_dwordx4 v[142:143], off
	s_waitcnt vmcnt(8)
	s_waitcnt lgkmcnt(0)
	s_barrier
	s_setprio 1
	s_waitcnt lgkmcnt(0)
	v_mfma_f32_16x16x32_bf16 v[64:67], v[138:141], v[176:179], v[64:67]
	v_mfma_f32_16x16x32_bf16 v[60:63], v[152:155], v[176:179], v[60:63]
	v_mfma_f32_16x16x32_bf16 v[48:51], v[138:141], v[184:187], v[48:51]
	v_mfma_f32_16x16x32_bf16 v[44:47], v[152:155], v[184:187], v[44:47]
	v_mfma_f32_16x16x32_bf16 v[32:35], v[138:141], v[192:195], v[32:35]
	v_mfma_f32_16x16x32_bf16 v[28:31], v[152:155], v[192:195], v[28:31]
	v_mfma_f32_16x16x32_bf16 v[20:23], v[138:141], v[200:203], v[20:23]
	v_mfma_f32_16x16x32_bf16 v[12:15], v[152:155], v[200:203], v[12:15]
	v_mfma_f32_16x16x32_bf16 v[64:67], v[148:151], v[180:183], v[64:67]
	v_mfma_f32_16x16x32_bf16 v[60:63], v[156:159], v[180:183], v[60:63]
	v_mfma_f32_16x16x32_bf16 v[48:51], v[148:151], v[188:191], v[48:51]
	v_mfma_f32_16x16x32_bf16 v[44:47], v[156:159], v[188:191], v[44:47]
	v_mfma_f32_16x16x32_bf16 v[32:35], v[148:151], v[196:199], v[32:35]
	v_mfma_f32_16x16x32_bf16 v[28:31], v[156:159], v[196:199], v[28:31]
	v_mfma_f32_16x16x32_bf16 v[20:23], v[148:151], v[204:207], v[20:23]
	v_mfma_f32_16x16x32_bf16 v[12:15], v[156:159], v[204:207], v[12:15]
	s_setprio 0
	s_setprio 1
	v_mfma_f32_16x16x32_bf16 v[56:59], v[160:163], v[176:179], v[56:59]
	v_mfma_f32_16x16x32_bf16 v[52:55], v[168:171], v[176:179], v[52:55]
	v_mfma_f32_16x16x32_bf16 v[40:43], v[160:163], v[184:187], v[40:43]
	v_mfma_f32_16x16x32_bf16 v[36:39], v[168:171], v[184:187], v[36:39]
	v_mfma_f32_16x16x32_bf16 v[24:27], v[160:163], v[192:195], v[24:27]
	v_mfma_f32_16x16x32_bf16 v[16:19], v[168:171], v[192:195], v[16:19]
	v_mfma_f32_16x16x32_bf16 v[8:11], v[160:163], v[200:203], v[8:11]
	v_mfma_f32_16x16x32_bf16 v[4:7], v[168:171], v[200:203], v[4:7]
	s_andn2_b64 vcc, exec, s[28:29]
	s_mov_b64 s[30:31], -1
	s_mov_b64 s[28:29], 0
	s_mov_b64 s[34:35], 0x100
	v_mfma_f32_16x16x32_bf16 v[56:59], v[164:167], v[180:183], v[56:59]
	v_mfma_f32_16x16x32_bf16 v[52:55], v[172:175], v[180:183], v[52:55]
	v_mfma_f32_16x16x32_bf16 v[40:43], v[164:167], v[188:191], v[40:43]
	v_mfma_f32_16x16x32_bf16 v[36:39], v[172:175], v[188:191], v[36:39]
	v_mfma_f32_16x16x32_bf16 v[24:27], v[164:167], v[196:199], v[24:27]
	v_mfma_f32_16x16x32_bf16 v[16:19], v[172:175], v[196:199], v[16:19]
	v_mfma_f32_16x16x32_bf16 v[8:11], v[164:167], v[204:207], v[8:11]
	v_mfma_f32_16x16x32_bf16 v[4:7], v[172:175], v[204:207], v[4:7]
	s_setprio 0
	s_barrier
	s_cbranch_vccz .LBB0_1564
	s_and_b64 vcc, exec, s[8:9]
	s_cbranch_vccz .LBB0_1567
	s_barrier

.LBB0_1649:
	s_add_i32 s58, 0, 0x10000
	s_add_i32 s60, 0, 0x14000
	v_add_u32_e32 v144, s58, v157
	v_add_u32_e32 v159, s60, v157
	ds_read_b128 v[132:135], v144
	ds_read_b128 v[136:139], v144 offset:1024
	ds_read_b128 v[140:143], v144 offset:2048
	ds_read_b128 v[144:147], v144 offset:3072
	ds_read_b128 v[164:167], v159
	ds_read_b128 v[168:171], v159 offset:1024
	ds_read_b128 v[172:175], v159 offset:2048
	ds_read_b128 v[176:179], v159 offset:3072
	ds_read_b128 v[180:183], v158
	ds_read_b128 v[184:187], v158 offset:1024
	ds_read_b128 v[188:191], v158 offset:2048
	ds_read_b128 v[192:195], v158 offset:3072
	ds_read_b128 v[196:199], v158 offset:4096
	ds_read_b128 v[200:203], v158 offset:5120
	ds_read_b128 v[204:207], v158 offset:6144
	ds_read_b128 v[230:233], v158 offset:7168
	s_add_u32 s28, s26, 0xfffc0080
	s_addc_u32 s29, s27, -1
	s_cmp_eq_u32 s57, 12
	s_cselect_b32 s31, s19, s29
	s_cselect_b32 s30, s53, s28
	s_cselect_b32 s29, s17, s56
	s_cselect_b32 s28, s54, s55
	v_lshl_add_u64 v[160:161], s[26:27], 0, v[154:155]
	s_add_i32 m0, s43, 0xc000
	s_nop 0
	global_load_lds_dwordx4 v[160:161], off
	v_lshl_add_u64 v[160:161], s[26:27], 0, v[162:163]
	s_add_i32 m0, s43, 0xe000
	s_nop 0
	global_load_lds_dwordx4 v[160:161], off
	s_waitcnt vmcnt(8)
	s_waitcnt lgkmcnt(0)
	s_barrier
	s_setprio 1
	s_waitcnt lgkmcnt(0)
	v_mfma_f32_16x16x32_bf16 v[128:131], v[132:135], v[180:183], v[128:131]
	v_mfma_f32_16x16x32_bf16 v[124:127], v[140:143], v[180:183], v[124:127]
	v_mfma_f32_16x16x32_bf16 v[112:115], v[132:135], v[188:191], v[112:115]
	v_mfma_f32_16x16x32_bf16 v[108:111], v[140:143], v[188:191], v[108:111]
	v_mfma_f32_16x16x32_bf16 v[96:99], v[132:135], v[196:199], v[96:99]
	v_mfma_f32_16x16x32_bf16 v[92:95], v[140:143], v[196:199], v[92:95]
	v_mfma_f32_16x16x32_bf16 v[80:83], v[132:135], v[204:207], v[80:83]
	v_mfma_f32_16x16x32_bf16 v[76:79], v[140:143], v[204:207], v[76:79]
	v_mfma_f32_16x16x32_bf16 v[128:131], v[136:139], v[184:187], v[128:131]
	v_mfma_f32_16x16x32_bf16 v[124:127], v[144:147], v[184:187], v[124:127]
	v_mfma_f32_16x16x32_bf16 v[112:115], v[136:139], v[192:195], v[112:115]
	v_mfma_f32_16x16x32_bf16 v[108:111], v[144:147], v[192:195], v[108:111]
	v_mfma_f32_16x16x32_bf16 v[96:99], v[136:139], v[200:203], v[96:99]
	v_mfma_f32_16x16x32_bf16 v[92:95], v[144:147], v[200:203], v[92:95]
	v_mfma_f32_16x16x32_bf16 v[80:83], v[136:139], v[230:233], v[80:83]
	v_mfma_f32_16x16x32_bf16 v[76:79], v[144:147], v[230:233], v[76:79]
	s_setprio 0
	s_setprio 1
	v_mfma_f32_16x16x32_bf16 v[120:123], v[164:167], v[180:183], v[120:123]
	v_mfma_f32_16x16x32_bf16 v[116:119], v[172:175], v[180:183], v[116:119]
	v_mfma_f32_16x16x32_bf16 v[104:107], v[164:167], v[188:191], v[104:107]
	v_mfma_f32_16x16x32_bf16 v[100:103], v[172:175], v[188:191], v[100:103]
	v_mfma_f32_16x16x32_bf16 v[88:91], v[164:167], v[196:199], v[88:91]
	v_mfma_f32_16x16x32_bf16 v[84:87], v[172:175], v[196:199], v[84:87]
	v_mfma_f32_16x16x32_bf16 v[72:75], v[164:167], v[204:207], v[72:75]
	v_mfma_f32_16x16x32_bf16 v[68:71], v[172:175], v[204:207], v[68:71]
	v_mfma_f32_16x16x32_bf16 v[120:123], v[168:171], v[184:187], v[120:123]
	v_mfma_f32_16x16x32_bf16 v[116:119], v[176:179], v[184:187], v[116:119]
	v_mfma_f32_16x16x32_bf16 v[104:107], v[168:171], v[192:195], v[104:107]
	v_mfma_f32_16x16x32_bf16 v[100:103], v[176:179], v[192:195], v[100:103]
	v_mfma_f32_16x16x32_bf16 v[88:91], v[168:171], v[200:203], v[88:91]
	v_mfma_f32_16x16x32_bf16 v[84:87], v[176:179], v[200:203], v[84:87]
	v_mfma_f32_16x16x32_bf16 v[72:75], v[168:171], v[230:233], v[72:75]
	v_mfma_f32_16x16x32_bf16 v[68:71], v[176:179], v[230:233], v[68:71]
	s_setprio 0
	s_barrier
	ds_read_b128 v[180:183], v158 offset:16384
	ds_read_b128 v[184:187], v158 offset:17408
	ds_read_b128 v[188:191], v158 offset:18432
	ds_read_b128 v[192:195], v158 offset:19456
	ds_read_b128 v[196:199], v158 offset:20480
	ds_read_b128 v[200:203], v158 offset:21504
	ds_read_b128 v[204:207], v158 offset:22528
	ds_read_b128 v[230:233], v158 offset:23552
	s_add_i32 s58, s58, s42
	v_lshl_add_u64 v[160:161], s[28:29], 0, v[150:151]
	s_mov_b32 m0, s58
	s_nop 0
	global_load_lds_dwordx4 v[160:161], off
	s_add_i32 m0, s58, 0x2000
	s_add_u32 s58, s28, 0x40000
	v_lshl_add_u64 v[208:209], s[28:29], 0, v[0:1]
	s_addc_u32 s59, s29, 0
	s_add_i32 s60, s60, s42
	global_load_lds_dwordx4 v[208:209], off
	v_lshl_add_u64 v[234:235], s[58:59], 0, v[150:151]
	s_mov_b32 m0, s60
	v_lshl_add_u64 v[240:241], s[30:31], 0, v[148:149]
	global_load_lds_dwordx4 v[234:235], off
	v_lshl_add_u64 v[234:235], s[58:59], 0, v[0:1]
	s_add_i32 m0, s60, 0x2000
	s_nop 0
	global_load_lds_dwordx4 v[234:235], off
	v_lshl_add_u64 v[234:235], s[30:31], 0, v[152:153]
	s_mov_b32 m0, s43
	s_nop 0
	global_load_lds_dwordx4 v[234:235], off
	s_mov_b32 m0, s44
	s_nop 0
	global_load_lds_dwordx4 v[240:241], off
	s_waitcnt vmcnt(8)
	s_waitcnt lgkmcnt(0)
	s_barrier
	s_setprio 1
	s_waitcnt lgkmcnt(0)
	v_mfma_f32_16x16x32_bf16 v[64:67], v[132:135], v[180:183], v[64:67]
	v_mfma_f32_16x16x32_bf16 v[60:63], v[140:143], v[180:183], v[60:63]
	v_mfma_f32_16x16x32_bf16 v[48:51], v[132:135], v[188:191], v[48:51]
	v_mfma_f32_16x16x32_bf16 v[44:47], v[140:143], v[188:191], v[44:47]
	v_mfma_f32_16x16x32_bf16 v[32:35], v[132:135], v[196:199], v[32:35]
	v_mfma_f32_16x16x32_bf16 v[28:31], v[140:143], v[196:199], v[28:31]
	v_mfma_f32_16x16x32_bf16 v[16:19], v[132:135], v[204:207], v[16:19]
	v_mfma_f32_16x16x32_bf16 v[12:15], v[140:143], v[204:207], v[12:15]
	v_mfma_f32_16x16x32_bf16 v[64:67], v[136:139], v[184:187], v[64:67]
	v_mfma_f32_16x16x32_bf16 v[60:63], v[144:147], v[184:187], v[60:63]
	v_mfma_f32_16x16x32_bf16 v[48:51], v[136:139], v[192:195], v[48:51]
	v_mfma_f32_16x16x32_bf16 v[44:47], v[144:147], v[192:195], v[44:47]
	v_mfma_f32_16x16x32_bf16 v[32:35], v[136:139], v[200:203], v[32:35]
	v_mfma_f32_16x16x32_bf16 v[28:31], v[144:147], v[200:203], v[28:31]
	v_mfma_f32_16x16x32_bf16 v[16:19], v[136:139], v[230:233], v[16:19]
	v_mfma_f32_16x16x32_bf16 v[12:15], v[144:147], v[230:233], v[12:15]
	s_setprio 0
	s_setprio 1
	v_mfma_f32_16x16x32_bf16 v[56:59], v[164:167], v[180:183], v[56:59]
	v_mfma_f32_16x16x32_bf16 v[52:55], v[172:175], v[180:183], v[52:55]
	v_mfma_f32_16x16x32_bf16 v[40:43], v[164:167], v[188:191], v[40:43]
	v_mfma_f32_16x16x32_bf16 v[36:39], v[172:175], v[188:191], v[36:39]
	v_mfma_f32_16x16x32_bf16 v[24:27], v[164:167], v[196:199], v[24:27]
	v_mfma_f32_16x16x32_bf16 v[20:23], v[172:175], v[196:199], v[20:23]
	v_mfma_f32_16x16x32_bf16 v[8:11], v[164:167], v[204:207], v[8:11]
	v_mfma_f32_16x16x32_bf16 v[4:7], v[172:175], v[204:207], v[4:7]
	v_mfma_f32_16x16x32_bf16 v[56:59], v[168:171], v[184:187], v[56:59]
	v_mfma_f32_16x16x32_bf16 v[52:55], v[176:179], v[184:187], v[52:55]
	v_mfma_f32_16x16x32_bf16 v[40:43], v[168:171], v[192:195], v[40:43]
	v_mfma_f32_16x16x32_bf16 v[36:39], v[176:179], v[192:195], v[36:39]
	v_mfma_f32_16x16x32_bf16 v[24:27], v[168:171], v[200:203], v[24:27]
	v_mfma_f32_16x16x32_bf16 v[20:23], v[176:179], v[200:203], v[20:23]
	v_mfma_f32_16x16x32_bf16 v[8:11], v[168:171], v[230:233], v[8:11]
	v_mfma_f32_16x16x32_bf16 v[4:7], v[176:179], v[230:233], v[4:7]
	s_setprio 0
	s_barrier
	s_add_i32 s58, 0, 0x18000
	s_add_i32 s59, 0, 0x1c000
	v_add_u32_e32 v144, s58, v157
	v_add_u32_e32 v159, s59, v157
	ds_read_b128 v[132:135], v144
	ds_read_b128 v[136:139], v144 offset:1024
	ds_read_b128 v[140:143], v144 offset:2048
	ds_read_b128 v[144:147], v144 offset:3072
	ds_read_b128 v[164:167], v159
	ds_read_b128 v[168:171], v159 offset:1024
	ds_read_b128 v[172:175], v159 offset:2048
	ds_read_b128 v[176:179], v159 offset:3072
	ds_read_b128 v[180:183], v158 offset:32768
	ds_read_b128 v[184:187], v158 offset:33792
	ds_read_b128 v[188:191], v158 offset:34816
	ds_read_b128 v[192:195], v158 offset:35840
	ds_read_b128 v[196:199], v158 offset:36864
	ds_read_b128 v[200:203], v158 offset:37888
	ds_read_b128 v[204:207], v158 offset:38912
	ds_read_b128 v[230:233], v158 offset:39936
	s_add_u32 s30, s30, 0x40000
	s_addc_u32 s31, s31, 0
	s_mov_b32 m0, s45
	v_lshl_add_u64 v[242:243], s[30:31], 0, v[152:153]
	global_load_lds_dwordx4 v[242:243], off
	v_lshl_add_u64 v[242:243], s[30:31], 0, v[148:149]
	s_mov_b32 m0, s46
	s_nop 0
	global_load_lds_dwordx4 v[242:243], off
	s_waitcnt vmcnt(8)
	s_waitcnt lgkmcnt(0)
	s_barrier
	s_setprio 1
	s_waitcnt lgkmcnt(0)
	v_mfma_f32_16x16x32_bf16 v[128:131], v[132:135], v[180:183], v[128:131]
	v_mfma_f32_16x16x32_bf16 v[124:127], v[140:143], v[180:183], v[124:127]
	v_mfma_f32_16x16x32_bf16 v[112:115], v[132:135], v[188:191], v[112:115]
	v_mfma_f32_16x16x32_bf16 v[108:111], v[140:143], v[188:191], v[108:111]
	v_mfma_f32_16x16x32_bf16 v[96:99], v[132:135], v[196:199], v[96:99]
	v_mfma_f32_16x16x32_bf16 v[92:95], v[140:143], v[196:199], v[92:95]
	v_mfma_f32_16x16x32_bf16 v[80:83], v[132:135], v[204:207], v[80:83]
	v_mfma_f32_16x16x32_bf16 v[76:79], v[140:143], v[204:207], v[76:79]
	v_mfma_f32_16x16x32_bf16 v[128:131], v[136:139], v[184:187], v[128:131]
	v_mfma_f32_16x16x32_bf16 v[124:127], v[144:147], v[184:187], v[124:127]
	v_mfma_f32_16x16x32_bf16 v[112:115], v[136:139], v[192:195], v[112:115]
	v_mfma_f32_16x16x32_bf16 v[108:111], v[144:147], v[192:195], v[108:111]
	v_mfma_f32_16x16x32_bf16 v[96:99], v[136:139], v[200:203], v[96:99]
	v_mfma_f32_16x16x32_bf16 v[92:95], v[144:147], v[200:203], v[92:95]
	v_mfma_f32_16x16x32_bf16 v[80:83], v[136:139], v[230:233], v[80:83]
	v_mfma_f32_16x16x32_bf16 v[76:79], v[144:147], v[230:233], v[76:79]
	s_setprio 0
	s_setprio 1
	v_mfma_f32_16x16x32_bf16 v[120:123], v[164:167], v[180:183], v[120:123]
	v_mfma_f32_16x16x32_bf16 v[116:119], v[172:175], v[180:183], v[116:119]
	v_mfma_f32_16x16x32_bf16 v[104:107], v[164:167], v[188:191], v[104:107]
	v_mfma_f32_16x16x32_bf16 v[100:103], v[172:175], v[188:191], v[100:103]
	v_mfma_f32_16x16x32_bf16 v[88:91], v[164:167], v[196:199], v[88:91]
	v_mfma_f32_16x16x32_bf16 v[84:87], v[172:175], v[196:199], v[84:87]
	v_mfma_f32_16x16x32_bf16 v[72:75], v[164:167], v[204:207], v[72:75]
	v_mfma_f32_16x16x32_bf16 v[68:71], v[172:175], v[204:207], v[68:71]
	v_mfma_f32_16x16x32_bf16 v[120:123], v[168:171], v[184:187], v[120:123]
	v_mfma_f32_16x16x32_bf16 v[116:119], v[176:179], v[184:187], v[116:119]
	v_mfma_f32_16x16x32_bf16 v[104:107], v[168:171], v[192:195], v[104:107]
	v_mfma_f32_16x16x32_bf16 v[100:103], v[176:179], v[192:195], v[100:103]
	v_mfma_f32_16x16x32_bf16 v[88:91], v[168:171], v[200:203], v[88:91]
	v_mfma_f32_16x16x32_bf16 v[84:87], v[176:179], v[200:203], v[84:87]
	v_mfma_f32_16x16x32_bf16 v[72:75], v[168:171], v[230:233], v[72:75]
	v_mfma_f32_16x16x32_bf16 v[68:71], v[176:179], v[230:233], v[68:71]
	s_setprio 0
	s_barrier
	ds_read_b128 v[180:183], v158 offset:49152
	ds_read_b128 v[184:187], v158 offset:50176
	ds_read_b128 v[188:191], v158 offset:51200
	ds_read_b128 v[192:195], v158 offset:52224
	ds_read_b128 v[196:199], v158 offset:53248
	ds_read_b128 v[200:203], v158 offset:54272
	ds_read_b128 v[204:207], v158 offset:55296
	ds_read_b128 v[230:233], v158 offset:56320
	s_add_i32 s30, s58, s42
	v_lshl_add_u64 v[160:161], v[160:161], 0, s[62:63]
	s_mov_b32 m0, s30
	s_nop 0
	global_load_lds_dwordx4 v[160:161], off
	s_add_i32 m0, s30, 0x2000
	s_add_u32 s28, s28, 0x40080
	v_lshl_add_u64 v[160:161], v[208:209], 0, s[62:63]
	s_addc_u32 s29, s29, 0
	s_add_i32 s30, s59, s42
	global_load_lds_dwordx4 v[160:161], off
	v_lshl_add_u64 v[160:161], s[28:29], 0, v[150:151]
	s_mov_b32 m0, s30
	s_nop 0
	global_load_lds_dwordx4 v[160:161], off
	v_lshl_add_u64 v[160:161], s[28:29], 0, v[0:1]
	s_add_i32 m0, s30, 0x2000
	s_nop 0
	global_load_lds_dwordx4 v[160:161], off
	v_lshl_add_u64 v[160:161], v[234:235], 0, s[62:63]
	s_mov_b32 m0, s49
	s_nop 0
	global_load_lds_dwordx4 v[160:161], off
	v_lshl_add_u64 v[160:161], v[240:241], 0, s[62:63]
	s_mov_b32 m0, s50
	s_nop 0
	global_load_lds_dwordx4 v[160:161], off
	s_waitcnt vmcnt(8)
	s_waitcnt lgkmcnt(0)
	s_barrier
	s_setprio 1
	s_waitcnt lgkmcnt(0)
	v_mfma_f32_16x16x32_bf16 v[64:67], v[132:135], v[180:183], v[64:67]
	v_mfma_f32_16x16x32_bf16 v[60:63], v[140:143], v[180:183], v[60:63]
	v_mfma_f32_16x16x32_bf16 v[48:51], v[132:135], v[188:191], v[48:51]
	v_mfma_f32_16x16x32_bf16 v[44:47], v[140:143], v[188:191], v[44:47]
	v_mfma_f32_16x16x32_bf16 v[32:35], v[132:135], v[196:199], v[32:35]
	v_mfma_f32_16x16x32_bf16 v[28:31], v[140:143], v[196:199], v[28:31]
	v_mfma_f32_16x16x32_bf16 v[16:19], v[132:135], v[204:207], v[16:19]
	v_mfma_f32_16x16x32_bf16 v[12:15], v[140:143], v[204:207], v[12:15]
	v_mfma_f32_16x16x32_bf16 v[64:67], v[136:139], v[184:187], v[64:67]
	v_mfma_f32_16x16x32_bf16 v[60:63], v[144:147], v[184:187], v[60:63]
	v_mfma_f32_16x16x32_bf16 v[48:51], v[136:139], v[192:195], v[48:51]
	v_mfma_f32_16x16x32_bf16 v[44:47], v[144:147], v[192:195], v[44:47]
	v_mfma_f32_16x16x32_bf16 v[32:35], v[136:139], v[200:203], v[32:35]
	v_mfma_f32_16x16x32_bf16 v[28:31], v[144:147], v[200:203], v[28:31]
	v_mfma_f32_16x16x32_bf16 v[16:19], v[136:139], v[230:233], v[16:19]
	v_mfma_f32_16x16x32_bf16 v[12:15], v[144:147], v[230:233], v[12:15]
	s_setprio 0
	s_setprio 1
	v_mfma_f32_16x16x32_bf16 v[56:59], v[164:167], v[180:183], v[56:59]
	v_mfma_f32_16x16x32_bf16 v[52:55], v[172:175], v[180:183], v[52:55]
	v_mfma_f32_16x16x32_bf16 v[40:43], v[164:167], v[188:191], v[40:43]
	v_mfma_f32_16x16x32_bf16 v[36:39], v[172:175], v[188:191], v[36:39]
	v_mfma_f32_16x16x32_bf16 v[24:27], v[164:167], v[196:199], v[24:27]
	v_mfma_f32_16x16x32_bf16 v[20:23], v[172:175], v[196:199], v[20:23]
	v_mfma_f32_16x16x32_bf16 v[8:11], v[164:167], v[204:207], v[8:11]
	v_mfma_f32_16x16x32_bf16 v[4:7], v[172:175], v[204:207], v[4:7]
	s_add_i32 s57, s57, 2
	s_add_u32 s26, s26, 0x100
	s_addc_u32 s27, s27, 0
	s_add_u32 s55, s55, 0x100
	s_addc_u32 s56, s56, 0
	s_cmp_gt_u32 s57, 13
	v_mfma_f32_16x16x32_bf16 v[56:59], v[168:171], v[184:187], v[56:59]
	v_mfma_f32_16x16x32_bf16 v[52:55], v[176:179], v[184:187], v[52:55]
	v_mfma_f32_16x16x32_bf16 v[40:43], v[168:171], v[192:195], v[40:43]
	v_mfma_f32_16x16x32_bf16 v[36:39], v[176:179], v[192:195], v[36:39]
	v_mfma_f32_16x16x32_bf16 v[24:27], v[168:171], v[200:203], v[24:27]
	v_mfma_f32_16x16x32_bf16 v[20:23], v[176:179], v[200:203], v[20:23]
	v_mfma_f32_16x16x32_bf16 v[8:11], v[168:171], v[230:233], v[8:11]
	v_mfma_f32_16x16x32_bf16 v[4:7], v[176:179], v[230:233], v[4:7]
	s_setprio 0
	s_barrier
	s_cbranch_scc0 .LBB0_1649
	s_and_b64 vcc, exec, s[8:9]
	s_cbranch_vccz .LBB0_1652
	s_barrier

.LBB0_1738:
	s_add_i32 s56, 0, 0x10000
	v_add_u32_e32 v157, s56, v155
	s_add_i32 s58, 0, 0x14000
	ds_read_b128 v[132:135], v157
	ds_read_b128 v[136:139], v157 offset:1024
	ds_read_b128 v[150:153], v157 offset:2048
	ds_read_b128 v[158:161], v157 offset:3072
	v_add_u32_e32 v157, s58, v155
	ds_read_b128 v[162:165], v157
	ds_read_b128 v[166:169], v157 offset:1024
	ds_read_b128 v[170:173], v157 offset:2048
	ds_read_b128 v[174:177], v157 offset:3072
	ds_read_b128 v[178:181], v156
	ds_read_b128 v[182:185], v156 offset:1024
	ds_read_b128 v[186:189], v156 offset:2048
	ds_read_b128 v[190:193], v156 offset:3072
	ds_read_b128 v[194:197], v156 offset:4096
	ds_read_b128 v[198:201], v156 offset:5120
	ds_read_b128 v[202:205], v156 offset:6144
	ds_read_b128 v[206:209], v156 offset:7168
	s_add_u32 s30, s4, 0xfffc0080
	s_addc_u32 s31, s5, -1
	s_cmp_eq_u32 s55, 12
	s_cselect_b32 s35, s19, s31
	s_cselect_b32 s34, s27, s30
	s_cselect_b32 s31, s17, s54
	s_cselect_b32 s30, s52, s53
	v_lshl_add_u64 v[230:231], s[4:5], 0, v[146:147]
	s_add_i32 m0, s29, 0xc000
	s_nop 0
	global_load_lds_dwordx4 v[230:231], off
	v_lshl_add_u64 v[230:231], s[4:5], 0, v[148:149]
	s_add_i32 m0, s29, 0xe000
	s_nop 0
	global_load_lds_dwordx4 v[230:231], off
	s_waitcnt vmcnt(8)
	s_waitcnt lgkmcnt(0)
	s_barrier
	s_setprio 1
	s_waitcnt lgkmcnt(0)
	v_mfma_f32_16x16x32_bf16 v[128:131], v[132:135], v[178:181], v[128:131]
	v_mfma_f32_16x16x32_bf16 v[124:127], v[150:153], v[178:181], v[124:127]
	v_mfma_f32_16x16x32_bf16 v[112:115], v[132:135], v[186:189], v[112:115]
	v_mfma_f32_16x16x32_bf16 v[108:111], v[150:153], v[186:189], v[108:111]
	v_mfma_f32_16x16x32_bf16 v[96:99], v[132:135], v[194:197], v[96:99]
	v_mfma_f32_16x16x32_bf16 v[92:95], v[150:153], v[194:197], v[92:95]
	v_mfma_f32_16x16x32_bf16 v[80:83], v[132:135], v[202:205], v[80:83]
	v_mfma_f32_16x16x32_bf16 v[76:79], v[150:153], v[202:205], v[76:79]
	v_mfma_f32_16x16x32_bf16 v[128:131], v[136:139], v[182:185], v[128:131]
	v_mfma_f32_16x16x32_bf16 v[124:127], v[158:161], v[182:185], v[124:127]
	v_mfma_f32_16x16x32_bf16 v[112:115], v[136:139], v[190:193], v[112:115]
	v_mfma_f32_16x16x32_bf16 v[108:111], v[158:161], v[190:193], v[108:111]
	v_mfma_f32_16x16x32_bf16 v[96:99], v[136:139], v[198:201], v[96:99]
	v_mfma_f32_16x16x32_bf16 v[92:95], v[158:161], v[198:201], v[92:95]
	v_mfma_f32_16x16x32_bf16 v[80:83], v[136:139], v[206:209], v[80:83]
	v_mfma_f32_16x16x32_bf16 v[76:79], v[158:161], v[206:209], v[76:79]
	s_setprio 0
	s_setprio 1
	v_mfma_f32_16x16x32_bf16 v[120:123], v[162:165], v[178:181], v[120:123]
	v_mfma_f32_16x16x32_bf16 v[116:119], v[170:173], v[178:181], v[116:119]
	v_mfma_f32_16x16x32_bf16 v[104:107], v[162:165], v[186:189], v[104:107]
	v_mfma_f32_16x16x32_bf16 v[100:103], v[170:173], v[186:189], v[100:103]
	v_mfma_f32_16x16x32_bf16 v[88:91], v[162:165], v[194:197], v[88:91]
	v_mfma_f32_16x16x32_bf16 v[84:87], v[170:173], v[194:197], v[84:87]
	v_mfma_f32_16x16x32_bf16 v[72:75], v[162:165], v[202:205], v[72:75]
	v_mfma_f32_16x16x32_bf16 v[68:71], v[170:173], v[202:205], v[68:71]
	v_mfma_f32_16x16x32_bf16 v[120:123], v[166:169], v[182:185], v[120:123]
	v_mfma_f32_16x16x32_bf16 v[116:119], v[174:177], v[182:185], v[116:119]
	v_mfma_f32_16x16x32_bf16 v[104:107], v[166:169], v[190:193], v[104:107]
	v_mfma_f32_16x16x32_bf16 v[100:103], v[174:177], v[190:193], v[100:103]
	v_mfma_f32_16x16x32_bf16 v[88:91], v[166:169], v[198:201], v[88:91]
	v_mfma_f32_16x16x32_bf16 v[84:87], v[174:177], v[198:201], v[84:87]
	v_mfma_f32_16x16x32_bf16 v[72:75], v[166:169], v[206:209], v[72:75]
	v_mfma_f32_16x16x32_bf16 v[68:71], v[174:177], v[206:209], v[68:71]
	s_setprio 0
	s_barrier
	ds_read_b128 v[178:181], v156 offset:16384
	ds_read_b128 v[182:185], v156 offset:17408
	ds_read_b128 v[186:189], v156 offset:18432
	ds_read_b128 v[190:193], v156 offset:19456
	ds_read_b128 v[194:197], v156 offset:20480
	ds_read_b128 v[198:201], v156 offset:21504
	ds_read_b128 v[202:205], v156 offset:22528
	ds_read_b128 v[206:209], v156 offset:23552
	s_add_i32 s56, s56, s43
	v_lshl_add_u64 v[230:231], s[30:31], 0, v[140:141]
	s_mov_b32 m0, s56
	s_nop 0
	global_load_lds_dwordx4 v[230:231], off
	s_add_i32 m0, s56, 0x2000
	s_add_u32 s56, s30, 0x40000
	v_lshl_add_u64 v[232:233], s[30:31], 0, v[144:145]
	s_addc_u32 s57, s31, 0
	s_add_i32 s58, s58, s43
	global_load_lds_dwordx4 v[232:233], off
	v_lshl_add_u64 v[234:235], s[56:57], 0, v[140:141]
	s_mov_b32 m0, s58
	v_lshl_add_u64 v[240:241], s[34:35], 0, v[142:143]
	global_load_lds_dwordx4 v[234:235], off
	v_lshl_add_u64 v[234:235], s[56:57], 0, v[144:145]
	s_add_i32 m0, s58, 0x2000
	s_nop 0
	global_load_lds_dwordx4 v[234:235], off
	v_lshl_add_u64 v[234:235], s[34:35], 0, v[0:1]
	s_mov_b32 m0, s29
	s_nop 0
	global_load_lds_dwordx4 v[234:235], off
	s_mov_b32 m0, s44
	s_nop 0
	global_load_lds_dwordx4 v[240:241], off
	s_waitcnt vmcnt(8)
	s_waitcnt lgkmcnt(0)
	s_barrier
	s_setprio 1
	s_waitcnt lgkmcnt(0)
	v_mfma_f32_16x16x32_bf16 v[64:67], v[132:135], v[178:181], v[64:67]
	v_mfma_f32_16x16x32_bf16 v[60:63], v[150:153], v[178:181], v[60:63]
	v_mfma_f32_16x16x32_bf16 v[48:51], v[132:135], v[186:189], v[48:51]
	v_mfma_f32_16x16x32_bf16 v[44:47], v[150:153], v[186:189], v[44:47]
	v_mfma_f32_16x16x32_bf16 v[32:35], v[132:135], v[194:197], v[32:35]
	v_mfma_f32_16x16x32_bf16 v[28:31], v[150:153], v[194:197], v[28:31]
	v_mfma_f32_16x16x32_bf16 v[16:19], v[132:135], v[202:205], v[16:19]
	v_mfma_f32_16x16x32_bf16 v[12:15], v[150:153], v[202:205], v[12:15]
	v_mfma_f32_16x16x32_bf16 v[64:67], v[136:139], v[182:185], v[64:67]
	v_mfma_f32_16x16x32_bf16 v[60:63], v[158:161], v[182:185], v[60:63]
	v_mfma_f32_16x16x32_bf16 v[48:51], v[136:139], v[190:193], v[48:51]
	v_mfma_f32_16x16x32_bf16 v[44:47], v[158:161], v[190:193], v[44:47]
	v_mfma_f32_16x16x32_bf16 v[32:35], v[136:139], v[198:201], v[32:35]
	v_mfma_f32_16x16x32_bf16 v[28:31], v[158:161], v[198:201], v[28:31]
	v_mfma_f32_16x16x32_bf16 v[16:19], v[136:139], v[206:209], v[16:19]
	v_mfma_f32_16x16x32_bf16 v[12:15], v[158:161], v[206:209], v[12:15]
	s_setprio 0
	s_setprio 1
	v_mfma_f32_16x16x32_bf16 v[56:59], v[162:165], v[178:181], v[56:59]
	v_mfma_f32_16x16x32_bf16 v[52:55], v[170:173], v[178:181], v[52:55]
	v_mfma_f32_16x16x32_bf16 v[40:43], v[162:165], v[186:189], v[40:43]
	v_mfma_f32_16x16x32_bf16 v[36:39], v[170:173], v[186:189], v[36:39]
	v_mfma_f32_16x16x32_bf16 v[24:27], v[162:165], v[194:197], v[24:27]
	v_mfma_f32_16x16x32_bf16 v[20:23], v[170:173], v[194:197], v[20:23]
	v_mfma_f32_16x16x32_bf16 v[8:11], v[162:165], v[202:205], v[8:11]
	v_mfma_f32_16x16x32_bf16 v[4:7], v[170:173], v[202:205], v[4:7]
	v_mfma_f32_16x16x32_bf16 v[56:59], v[166:169], v[182:185], v[56:59]
	v_mfma_f32_16x16x32_bf16 v[52:55], v[174:177], v[182:185], v[52:55]
	v_mfma_f32_16x16x32_bf16 v[40:43], v[166:169], v[190:193], v[40:43]
	v_mfma_f32_16x16x32_bf16 v[36:39], v[174:177], v[190:193], v[36:39]
	v_mfma_f32_16x16x32_bf16 v[24:27], v[166:169], v[198:201], v[24:27]
	v_mfma_f32_16x16x32_bf16 v[20:23], v[174:177], v[198:201], v[20:23]
	v_mfma_f32_16x16x32_bf16 v[8:11], v[166:169], v[206:209], v[8:11]
	v_mfma_f32_16x16x32_bf16 v[4:7], v[174:177], v[206:209], v[4:7]
	s_setprio 0
	s_barrier
	s_add_i32 s56, 0, 0x18000
	v_add_u32_e32 v157, s56, v155
	s_add_i32 s57, 0, 0x1c000
	ds_read_b128 v[132:135], v157
	ds_read_b128 v[136:139], v157 offset:1024
	ds_read_b128 v[150:153], v157 offset:2048
	ds_read_b128 v[158:161], v157 offset:3072
	v_add_u32_e32 v157, s57, v155
	ds_read_b128 v[162:165], v157
	ds_read_b128 v[166:169], v157 offset:1024
	ds_read_b128 v[170:173], v157 offset:2048
	ds_read_b128 v[174:177], v157 offset:3072
	ds_read_b128 v[178:181], v156 offset:32768
	ds_read_b128 v[182:185], v156 offset:33792
	ds_read_b128 v[186:189], v156 offset:34816
	ds_read_b128 v[190:193], v156 offset:35840
	ds_read_b128 v[194:197], v156 offset:36864
	ds_read_b128 v[198:201], v156 offset:37888
	ds_read_b128 v[202:205], v156 offset:38912
	ds_read_b128 v[206:209], v156 offset:39936
	s_add_u32 s34, s34, 0x40000
	s_addc_u32 s35, s35, 0
	s_mov_b32 m0, s45
	v_lshl_add_u64 v[242:243], s[34:35], 0, v[0:1]
	global_load_lds_dwordx4 v[242:243], off
	v_lshl_add_u64 v[242:243], s[34:35], 0, v[142:143]
	s_mov_b32 m0, s46
	s_nop 0
	global_load_lds_dwordx4 v[242:243], off
	s_waitcnt vmcnt(8)
	s_waitcnt lgkmcnt(0)
	s_barrier
	s_setprio 1
	s_waitcnt lgkmcnt(0)
	v_mfma_f32_16x16x32_bf16 v[128:131], v[132:135], v[178:181], v[128:131]
	v_mfma_f32_16x16x32_bf16 v[124:127], v[150:153], v[178:181], v[124:127]
	v_mfma_f32_16x16x32_bf16 v[112:115], v[132:135], v[186:189], v[112:115]
	v_mfma_f32_16x16x32_bf16 v[108:111], v[150:153], v[186:189], v[108:111]
	v_mfma_f32_16x16x32_bf16 v[96:99], v[132:135], v[194:197], v[96:99]
	v_mfma_f32_16x16x32_bf16 v[92:95], v[150:153], v[194:197], v[92:95]
	v_mfma_f32_16x16x32_bf16 v[80:83], v[132:135], v[202:205], v[80:83]
	v_mfma_f32_16x16x32_bf16 v[76:79], v[150:153], v[202:205], v[76:79]
	v_mfma_f32_16x16x32_bf16 v[128:131], v[136:139], v[182:185], v[128:131]
	v_mfma_f32_16x16x32_bf16 v[124:127], v[158:161], v[182:185], v[124:127]
	v_mfma_f32_16x16x32_bf16 v[112:115], v[136:139], v[190:193], v[112:115]
	v_mfma_f32_16x16x32_bf16 v[108:111], v[158:161], v[190:193], v[108:111]
	v_mfma_f32_16x16x32_bf16 v[96:99], v[136:139], v[198:201], v[96:99]
	v_mfma_f32_16x16x32_bf16 v[92:95], v[158:161], v[198:201], v[92:95]
	v_mfma_f32_16x16x32_bf16 v[80:83], v[136:139], v[206:209], v[80:83]
	v_mfma_f32_16x16x32_bf16 v[76:79], v[158:161], v[206:209], v[76:79]
	s_setprio 0
	s_setprio 1
	v_mfma_f32_16x16x32_bf16 v[120:123], v[162:165], v[178:181], v[120:123]
	v_mfma_f32_16x16x32_bf16 v[116:119], v[170:173], v[178:181], v[116:119]
	v_mfma_f32_16x16x32_bf16 v[104:107], v[162:165], v[186:189], v[104:107]
	v_mfma_f32_16x16x32_bf16 v[100:103], v[170:173], v[186:189], v[100:103]
	v_mfma_f32_16x16x32_bf16 v[88:91], v[162:165], v[194:197], v[88:91]
	v_mfma_f32_16x16x32_bf16 v[84:87], v[170:173], v[194:197], v[84:87]
	v_mfma_f32_16x16x32_bf16 v[72:75], v[162:165], v[202:205], v[72:75]
	v_mfma_f32_16x16x32_bf16 v[68:71], v[170:173], v[202:205], v[68:71]
	v_mfma_f32_16x16x32_bf16 v[120:123], v[166:169], v[182:185], v[120:123]
	v_mfma_f32_16x16x32_bf16 v[116:119], v[174:177], v[182:185], v[116:119]
	v_mfma_f32_16x16x32_bf16 v[104:107], v[166:169], v[190:193], v[104:107]
	v_mfma_f32_16x16x32_bf16 v[100:103], v[174:177], v[190:193], v[100:103]
	v_mfma_f32_16x16x32_bf16 v[88:91], v[166:169], v[198:201], v[88:91]
	v_mfma_f32_16x16x32_bf16 v[84:87], v[174:177], v[198:201], v[84:87]
	v_mfma_f32_16x16x32_bf16 v[72:75], v[166:169], v[206:209], v[72:75]
	v_mfma_f32_16x16x32_bf16 v[68:71], v[174:177], v[206:209], v[68:71]
	s_setprio 0
	s_barrier
	ds_read_b128 v[178:181], v156 offset:49152
	ds_read_b128 v[182:185], v156 offset:50176
	ds_read_b128 v[186:189], v156 offset:51200
	ds_read_b128 v[190:193], v156 offset:52224
	ds_read_b128 v[194:197], v156 offset:53248
	ds_read_b128 v[198:201], v156 offset:54272
	ds_read_b128 v[202:205], v156 offset:55296
	ds_read_b128 v[206:209], v156 offset:56320
	s_add_i32 s34, s56, s43
	v_lshl_add_u64 v[230:231], v[230:231], 0, s[60:61]
	s_mov_b32 m0, s34
	s_nop 0
	global_load_lds_dwordx4 v[230:231], off
	s_add_i32 m0, s34, 0x2000
	s_add_u32 s30, s30, 0x40080
	v_lshl_add_u64 v[230:231], v[232:233], 0, s[60:61]
	s_addc_u32 s31, s31, 0
	s_add_i32 s34, s57, s43
	global_load_lds_dwordx4 v[230:231], off
	v_lshl_add_u64 v[230:231], s[30:31], 0, v[140:141]
	s_mov_b32 m0, s34
	s_nop 0
	global_load_lds_dwordx4 v[230:231], off
	v_lshl_add_u64 v[230:231], s[30:31], 0, v[144:145]
	s_add_i32 m0, s34, 0x2000
	s_nop 0
	global_load_lds_dwordx4 v[230:231], off
	v_lshl_add_u64 v[230:231], v[234:235], 0, s[60:61]
	s_mov_b32 m0, s49
	s_nop 0
	global_load_lds_dwordx4 v[230:231], off
	v_lshl_add_u64 v[230:231], v[240:241], 0, s[60:61]
	s_mov_b32 m0, s50
	s_nop 0
	global_load_lds_dwordx4 v[230:231], off
	s_waitcnt vmcnt(8)
	s_waitcnt lgkmcnt(0)
	s_barrier
	s_setprio 1
	s_waitcnt lgkmcnt(0)
	v_mfma_f32_16x16x32_bf16 v[64:67], v[132:135], v[178:181], v[64:67]
	v_mfma_f32_16x16x32_bf16 v[60:63], v[150:153], v[178:181], v[60:63]
	v_mfma_f32_16x16x32_bf16 v[48:51], v[132:135], v[186:189], v[48:51]
	v_mfma_f32_16x16x32_bf16 v[44:47], v[150:153], v[186:189], v[44:47]
	v_mfma_f32_16x16x32_bf16 v[32:35], v[132:135], v[194:197], v[32:35]
	v_mfma_f32_16x16x32_bf16 v[28:31], v[150:153], v[194:197], v[28:31]
	v_mfma_f32_16x16x32_bf16 v[16:19], v[132:135], v[202:205], v[16:19]
	v_mfma_f32_16x16x32_bf16 v[12:15], v[150:153], v[202:205], v[12:15]
	v_mfma_f32_16x16x32_bf16 v[64:67], v[136:139], v[182:185], v[64:67]
	v_mfma_f32_16x16x32_bf16 v[60:63], v[158:161], v[182:185], v[60:63]
	v_mfma_f32_16x16x32_bf16 v[48:51], v[136:139], v[190:193], v[48:51]
	v_mfma_f32_16x16x32_bf16 v[44:47], v[158:161], v[190:193], v[44:47]
	v_mfma_f32_16x16x32_bf16 v[32:35], v[136:139], v[198:201], v[32:35]
	v_mfma_f32_16x16x32_bf16 v[28:31], v[158:161], v[198:201], v[28:31]
	v_mfma_f32_16x16x32_bf16 v[16:19], v[136:139], v[206:209], v[16:19]
	v_mfma_f32_16x16x32_bf16 v[12:15], v[158:161], v[206:209], v[12:15]
	s_setprio 0
	s_setprio 1
	v_mfma_f32_16x16x32_bf16 v[56:59], v[162:165], v[178:181], v[56:59]
	v_mfma_f32_16x16x32_bf16 v[52:55], v[170:173], v[178:181], v[52:55]
	v_mfma_f32_16x16x32_bf16 v[40:43], v[162:165], v[186:189], v[40:43]
	v_mfma_f32_16x16x32_bf16 v[36:39], v[170:173], v[186:189], v[36:39]
	v_mfma_f32_16x16x32_bf16 v[24:27], v[162:165], v[194:197], v[24:27]
	v_mfma_f32_16x16x32_bf16 v[20:23], v[170:173], v[194:197], v[20:23]
	v_mfma_f32_16x16x32_bf16 v[8:11], v[162:165], v[202:205], v[8:11]
	v_mfma_f32_16x16x32_bf16 v[4:7], v[170:173], v[202:205], v[4:7]
	s_add_i32 s55, s55, 2
	s_add_u32 s4, s4, 0x100
	s_addc_u32 s5, s5, 0
	s_add_u32 s53, s53, 0x100
	s_addc_u32 s54, s54, 0
	s_cmp_gt_u32 s55, 13
	v_mfma_f32_16x16x32_bf16 v[56:59], v[166:169], v[182:185], v[56:59]
	v_mfma_f32_16x16x32_bf16 v[52:55], v[174:177], v[182:185], v[52:55]
	v_mfma_f32_16x16x32_bf16 v[40:43], v[166:169], v[190:193], v[40:43]
	v_mfma_f32_16x16x32_bf16 v[36:39], v[174:177], v[190:193], v[36:39]
	v_mfma_f32_16x16x32_bf16 v[24:27], v[166:169], v[198:201], v[24:27]
	v_mfma_f32_16x16x32_bf16 v[20:23], v[174:177], v[198:201], v[20:23]
	v_mfma_f32_16x16x32_bf16 v[8:11], v[166:169], v[206:209], v[8:11]
	v_mfma_f32_16x16x32_bf16 v[4:7], v[174:177], v[206:209], v[4:7]
	s_setprio 0
	s_barrier
	s_cbranch_scc0 .LBB0_1738
	s_and_b64 vcc, exec, s[14:15]
	s_cbranch_vccz .LBB0_1741
	s_barrier

.LBB0_1875:
	s_add_i32 s75, 0, 0x10000
	v_add_u32_e32 v2, s75, v149
	s_add_i32 s78, 0, 0x14000
	ds_read_b128 v[152:155], v2
	ds_read_b128 v[156:159], v2 offset:1024
	ds_read_b128 v[160:163], v2 offset:2048
	ds_read_b128 v[164:167], v2 offset:3072
	v_add_u32_e32 v2, s78, v149
	ds_read_b128 v[168:171], v2
	ds_read_b128 v[172:175], v2 offset:1024
	ds_read_b128 v[176:179], v2 offset:2048
	ds_read_b128 v[180:183], v2 offset:3072
	ds_read_b128 v[184:187], v151
	ds_read_b128 v[188:191], v151 offset:1024
	ds_read_b128 v[192:195], v151 offset:2048
	ds_read_b128 v[196:199], v151 offset:3072
	ds_read_b128 v[200:203], v151 offset:4096
	ds_read_b128 v[204:207], v151 offset:5120
	ds_read_b128 v[230:233], v151 offset:6144
	ds_read_b128 v[240:243], v151 offset:7168
	s_add_u32 s50, s4, 0xfffc0080
	s_addc_u32 s51, s5, -1
	s_cmp_eq_u32 s74, 12
	s_cselect_b32 s53, s31, s51
	s_cselect_b32 s52, s37, s50
	s_cselect_b32 s51, s29, s73
	s_cselect_b32 s50, s49, s72
	v_lshl_add_u64 v[142:143], s[4:5], 0, v[138:139]
	s_add_i32 m0, s47, 0xc000
	s_nop 0
	global_load_lds_dwordx4 v[142:143], off
	v_lshl_add_u64 v[142:143], s[4:5], 0, v[140:141]
	s_add_i32 m0, s47, 0xe000
	s_nop 0
	global_load_lds_dwordx4 v[142:143], off
	s_waitcnt vmcnt(8)
	s_waitcnt lgkmcnt(0)
	s_barrier
	s_setprio 1
	s_waitcnt lgkmcnt(0)
	v_mfma_f32_16x16x32_bf16 v[128:131], v[152:155], v[184:187], v[128:131]
	v_mfma_f32_16x16x32_bf16 v[124:127], v[160:163], v[184:187], v[124:127]
	v_mfma_f32_16x16x32_bf16 v[112:115], v[152:155], v[192:195], v[112:115]
	v_mfma_f32_16x16x32_bf16 v[108:111], v[160:163], v[192:195], v[108:111]
	v_mfma_f32_16x16x32_bf16 v[96:99], v[152:155], v[200:203], v[96:99]
	v_mfma_f32_16x16x32_bf16 v[92:95], v[160:163], v[200:203], v[92:95]
	v_mfma_f32_16x16x32_bf16 v[80:83], v[152:155], v[230:233], v[80:83]
	v_mfma_f32_16x16x32_bf16 v[76:79], v[160:163], v[230:233], v[76:79]
	v_mfma_f32_16x16x32_bf16 v[128:131], v[156:159], v[188:191], v[128:131]
	v_mfma_f32_16x16x32_bf16 v[124:127], v[164:167], v[188:191], v[124:127]
	v_mfma_f32_16x16x32_bf16 v[112:115], v[156:159], v[196:199], v[112:115]
	v_mfma_f32_16x16x32_bf16 v[108:111], v[164:167], v[196:199], v[108:111]
	v_mfma_f32_16x16x32_bf16 v[96:99], v[156:159], v[204:207], v[96:99]
	v_mfma_f32_16x16x32_bf16 v[92:95], v[164:167], v[204:207], v[92:95]
	v_mfma_f32_16x16x32_bf16 v[80:83], v[156:159], v[240:243], v[80:83]
	v_mfma_f32_16x16x32_bf16 v[76:79], v[164:167], v[240:243], v[76:79]
	s_setprio 0
	s_setprio 1
	v_mfma_f32_16x16x32_bf16 v[120:123], v[168:171], v[184:187], v[120:123]
	v_mfma_f32_16x16x32_bf16 v[116:119], v[176:179], v[184:187], v[116:119]
	v_mfma_f32_16x16x32_bf16 v[104:107], v[168:171], v[192:195], v[104:107]
	v_mfma_f32_16x16x32_bf16 v[100:103], v[176:179], v[192:195], v[100:103]
	v_mfma_f32_16x16x32_bf16 v[88:91], v[168:171], v[200:203], v[88:91]
	v_mfma_f32_16x16x32_bf16 v[84:87], v[176:179], v[200:203], v[84:87]
	v_mfma_f32_16x16x32_bf16 v[72:75], v[168:171], v[230:233], v[72:75]
	v_mfma_f32_16x16x32_bf16 v[68:71], v[176:179], v[230:233], v[68:71]
	v_mfma_f32_16x16x32_bf16 v[120:123], v[172:175], v[188:191], v[120:123]
	v_mfma_f32_16x16x32_bf16 v[116:119], v[180:183], v[188:191], v[116:119]
	v_mfma_f32_16x16x32_bf16 v[104:107], v[172:175], v[196:199], v[104:107]
	v_mfma_f32_16x16x32_bf16 v[100:103], v[180:183], v[196:199], v[100:103]
	v_mfma_f32_16x16x32_bf16 v[88:91], v[172:175], v[204:207], v[88:91]
	v_mfma_f32_16x16x32_bf16 v[84:87], v[180:183], v[204:207], v[84:87]
	v_mfma_f32_16x16x32_bf16 v[72:75], v[172:175], v[240:243], v[72:75]
	v_mfma_f32_16x16x32_bf16 v[68:71], v[180:183], v[240:243], v[68:71]
	s_setprio 0
	s_barrier
	ds_read_b128 v[184:187], v151 offset:16384
	ds_read_b128 v[188:191], v151 offset:17408
	ds_read_b128 v[192:195], v151 offset:18432
	ds_read_b128 v[196:199], v151 offset:19456
	ds_read_b128 v[200:203], v151 offset:20480
	ds_read_b128 v[204:207], v151 offset:21504
	ds_read_b128 v[230:233], v151 offset:22528
	ds_read_b128 v[240:243], v151 offset:23552
	s_add_i32 s75, s75, s60
	v_lshl_add_u64 v[142:143], s[50:51], 0, v[132:133]
	s_mov_b32 m0, s75
	s_nop 0
	global_load_lds_dwordx4 v[142:143], off
	s_add_i32 m0, s75, 0x2000
	s_add_u32 s76, s50, 0x40000
	v_lshl_add_u64 v[208:209], s[50:51], 0, v[136:137]
	s_addc_u32 s77, s51, 0
	s_add_i32 s75, s78, s60
	global_load_lds_dwordx4 v[208:209], off
	v_lshl_add_u64 v[234:235], s[76:77], 0, v[132:133]
	s_mov_b32 m0, s75
	v_lshl_add_u64 v[244:245], s[52:53], 0, v[134:135]
	global_load_lds_dwordx4 v[234:235], off
	v_lshl_add_u64 v[234:235], s[76:77], 0, v[136:137]
	s_add_i32 m0, s75, 0x2000
	s_nop 0
	global_load_lds_dwordx4 v[234:235], off
	v_lshl_add_u64 v[234:235], s[52:53], 0, v[0:1]
	s_mov_b32 m0, s47
	s_nop 0
	global_load_lds_dwordx4 v[234:235], off
	s_mov_b32 m0, s63
	s_nop 0
	global_load_lds_dwordx4 v[244:245], off
	s_waitcnt vmcnt(8)
	s_waitcnt lgkmcnt(0)
	s_barrier
	s_setprio 1
	s_waitcnt lgkmcnt(0)
	v_mfma_f32_16x16x32_bf16 v[64:67], v[152:155], v[184:187], v[64:67]
	v_mfma_f32_16x16x32_bf16 v[60:63], v[160:163], v[184:187], v[60:63]
	v_mfma_f32_16x16x32_bf16 v[48:51], v[152:155], v[192:195], v[48:51]
	v_mfma_f32_16x16x32_bf16 v[44:47], v[160:163], v[192:195], v[44:47]
	v_mfma_f32_16x16x32_bf16 v[32:35], v[152:155], v[200:203], v[32:35]
	v_mfma_f32_16x16x32_bf16 v[28:31], v[160:163], v[200:203], v[28:31]
	v_mfma_f32_16x16x32_bf16 v[16:19], v[152:155], v[230:233], v[16:19]
	v_mfma_f32_16x16x32_bf16 v[12:15], v[160:163], v[230:233], v[12:15]
	v_mfma_f32_16x16x32_bf16 v[64:67], v[156:159], v[188:191], v[64:67]
	v_mfma_f32_16x16x32_bf16 v[60:63], v[164:167], v[188:191], v[60:63]
	v_mfma_f32_16x16x32_bf16 v[48:51], v[156:159], v[196:199], v[48:51]
	v_mfma_f32_16x16x32_bf16 v[44:47], v[164:167], v[196:199], v[44:47]
	v_mfma_f32_16x16x32_bf16 v[32:35], v[156:159], v[204:207], v[32:35]
	v_mfma_f32_16x16x32_bf16 v[28:31], v[164:167], v[204:207], v[28:31]
	v_mfma_f32_16x16x32_bf16 v[16:19], v[156:159], v[240:243], v[16:19]
	v_mfma_f32_16x16x32_bf16 v[12:15], v[164:167], v[240:243], v[12:15]
	s_setprio 0
	s_setprio 1
	v_mfma_f32_16x16x32_bf16 v[56:59], v[168:171], v[184:187], v[56:59]
	v_mfma_f32_16x16x32_bf16 v[52:55], v[176:179], v[184:187], v[52:55]
	v_mfma_f32_16x16x32_bf16 v[40:43], v[168:171], v[192:195], v[40:43]
	v_mfma_f32_16x16x32_bf16 v[36:39], v[176:179], v[192:195], v[36:39]
	v_mfma_f32_16x16x32_bf16 v[24:27], v[168:171], v[200:203], v[24:27]
	v_mfma_f32_16x16x32_bf16 v[20:23], v[176:179], v[200:203], v[20:23]
	v_mfma_f32_16x16x32_bf16 v[8:11], v[168:171], v[230:233], v[8:11]
	v_mfma_f32_16x16x32_bf16 v[4:7], v[176:179], v[230:233], v[4:7]
	v_mfma_f32_16x16x32_bf16 v[56:59], v[172:175], v[188:191], v[56:59]
	v_mfma_f32_16x16x32_bf16 v[52:55], v[180:183], v[188:191], v[52:55]
	v_mfma_f32_16x16x32_bf16 v[40:43], v[172:175], v[196:199], v[40:43]
	v_mfma_f32_16x16x32_bf16 v[36:39], v[180:183], v[196:199], v[36:39]
	v_mfma_f32_16x16x32_bf16 v[24:27], v[172:175], v[204:207], v[24:27]
	v_mfma_f32_16x16x32_bf16 v[20:23], v[180:183], v[204:207], v[20:23]
	v_mfma_f32_16x16x32_bf16 v[8:11], v[172:175], v[240:243], v[8:11]
	v_mfma_f32_16x16x32_bf16 v[4:7], v[180:183], v[240:243], v[4:7]
	s_setprio 0
	s_barrier
	s_add_i32 s75, 0, 0x18000
	v_add_u32_e32 v2, s75, v149
	s_add_i32 s76, 0, 0x1c000
	ds_read_b128 v[152:155], v2
	ds_read_b128 v[156:159], v2 offset:1024
	ds_read_b128 v[160:163], v2 offset:2048
	ds_read_b128 v[164:167], v2 offset:3072
	v_add_u32_e32 v2, s76, v149
	ds_read_b128 v[168:171], v2
	ds_read_b128 v[172:175], v2 offset:1024
	ds_read_b128 v[176:179], v2 offset:2048
	ds_read_b128 v[180:183], v2 offset:3072
	ds_read_b128 v[184:187], v151 offset:32768
	ds_read_b128 v[188:191], v151 offset:33792
	ds_read_b128 v[192:195], v151 offset:34816
	ds_read_b128 v[196:199], v151 offset:35840
	ds_read_b128 v[200:203], v151 offset:36864
	ds_read_b128 v[204:207], v151 offset:37888
	ds_read_b128 v[230:233], v151 offset:38912
	ds_read_b128 v[240:243], v151 offset:39936
	s_add_u32 s52, s52, 0x40000
	s_addc_u32 s53, s53, 0
	s_mov_b32 m0, s64
	v_lshl_add_u64 v[246:247], s[52:53], 0, v[0:1]
	global_load_lds_dwordx4 v[246:247], off
	v_lshl_add_u64 v[246:247], s[52:53], 0, v[134:135]
	s_mov_b32 m0, s65
	s_nop 0
	global_load_lds_dwordx4 v[246:247], off
	s_waitcnt vmcnt(8)
	s_waitcnt lgkmcnt(0)
	s_barrier
	s_setprio 1
	s_waitcnt lgkmcnt(0)
	v_mfma_f32_16x16x32_bf16 v[128:131], v[152:155], v[184:187], v[128:131]
	v_mfma_f32_16x16x32_bf16 v[124:127], v[160:163], v[184:187], v[124:127]
	v_mfma_f32_16x16x32_bf16 v[112:115], v[152:155], v[192:195], v[112:115]
	v_mfma_f32_16x16x32_bf16 v[108:111], v[160:163], v[192:195], v[108:111]
	v_mfma_f32_16x16x32_bf16 v[96:99], v[152:155], v[200:203], v[96:99]
	v_mfma_f32_16x16x32_bf16 v[92:95], v[160:163], v[200:203], v[92:95]
	v_mfma_f32_16x16x32_bf16 v[80:83], v[152:155], v[230:233], v[80:83]
	v_mfma_f32_16x16x32_bf16 v[76:79], v[160:163], v[230:233], v[76:79]
	v_mfma_f32_16x16x32_bf16 v[128:131], v[156:159], v[188:191], v[128:131]
	v_mfma_f32_16x16x32_bf16 v[124:127], v[164:167], v[188:191], v[124:127]
	v_mfma_f32_16x16x32_bf16 v[112:115], v[156:159], v[196:199], v[112:115]
	v_mfma_f32_16x16x32_bf16 v[108:111], v[164:167], v[196:199], v[108:111]
	v_mfma_f32_16x16x32_bf16 v[96:99], v[156:159], v[204:207], v[96:99]
	v_mfma_f32_16x16x32_bf16 v[92:95], v[164:167], v[204:207], v[92:95]
	v_mfma_f32_16x16x32_bf16 v[80:83], v[156:159], v[240:243], v[80:83]
	v_mfma_f32_16x16x32_bf16 v[76:79], v[164:167], v[240:243], v[76:79]
	s_setprio 0
	s_setprio 1
	v_mfma_f32_16x16x32_bf16 v[120:123], v[168:171], v[184:187], v[120:123]
	v_mfma_f32_16x16x32_bf16 v[116:119], v[176:179], v[184:187], v[116:119]
	v_mfma_f32_16x16x32_bf16 v[104:107], v[168:171], v[192:195], v[104:107]
	v_mfma_f32_16x16x32_bf16 v[100:103], v[176:179], v[192:195], v[100:103]
	v_mfma_f32_16x16x32_bf16 v[88:91], v[168:171], v[200:203], v[88:91]
	v_mfma_f32_16x16x32_bf16 v[84:87], v[176:179], v[200:203], v[84:87]
	v_mfma_f32_16x16x32_bf16 v[72:75], v[168:171], v[230:233], v[72:75]
	v_mfma_f32_16x16x32_bf16 v[68:71], v[176:179], v[230:233], v[68:71]
	v_mfma_f32_16x16x32_bf16 v[120:123], v[172:175], v[188:191], v[120:123]
	v_mfma_f32_16x16x32_bf16 v[116:119], v[180:183], v[188:191], v[116:119]
	v_mfma_f32_16x16x32_bf16 v[104:107], v[172:175], v[196:199], v[104:107]
	v_mfma_f32_16x16x32_bf16 v[100:103], v[180:183], v[196:199], v[100:103]
	v_mfma_f32_16x16x32_bf16 v[88:91], v[172:175], v[204:207], v[88:91]
	v_mfma_f32_16x16x32_bf16 v[84:87], v[180:183], v[204:207], v[84:87]
	v_mfma_f32_16x16x32_bf16 v[72:75], v[172:175], v[240:243], v[72:75]
	v_mfma_f32_16x16x32_bf16 v[68:71], v[180:183], v[240:243], v[68:71]
	s_setprio 0
	s_barrier
	ds_read_b128 v[184:187], v151 offset:49152
	ds_read_b128 v[188:191], v151 offset:50176
	ds_read_b128 v[192:195], v151 offset:51200
	ds_read_b128 v[196:199], v151 offset:52224
	ds_read_b128 v[200:203], v151 offset:53248
	ds_read_b128 v[204:207], v151 offset:54272
	ds_read_b128 v[230:233], v151 offset:55296
	ds_read_b128 v[240:243], v151 offset:56320
	s_add_i32 s52, s75, s60
	v_lshl_add_u64 v[142:143], v[142:143], 0, s[82:83]
	s_mov_b32 m0, s52
	s_nop 0
	global_load_lds_dwordx4 v[142:143], off
	s_add_i32 m0, s52, 0x2000
	s_add_u32 s50, s50, 0x40080
	v_lshl_add_u64 v[142:143], v[208:209], 0, s[82:83]
	s_addc_u32 s51, s51, 0
	s_add_i32 s52, s76, s60
	global_load_lds_dwordx4 v[142:143], off
	v_lshl_add_u64 v[142:143], s[50:51], 0, v[132:133]
	s_mov_b32 m0, s52
	s_nop 0
	global_load_lds_dwordx4 v[142:143], off
	v_lshl_add_u64 v[142:143], s[50:51], 0, v[136:137]
	s_add_i32 m0, s52, 0x2000
	s_nop 0
	global_load_lds_dwordx4 v[142:143], off
	v_lshl_add_u64 v[142:143], v[234:235], 0, s[82:83]
	s_mov_b32 m0, s68
	s_nop 0
	global_load_lds_dwordx4 v[142:143], off
	v_lshl_add_u64 v[142:143], v[244:245], 0, s[82:83]
	s_mov_b32 m0, s69
	s_nop 0
	global_load_lds_dwordx4 v[142:143], off
	s_waitcnt vmcnt(8)
	s_waitcnt lgkmcnt(0)
	s_barrier
	s_setprio 1
	s_waitcnt lgkmcnt(0)
	v_mfma_f32_16x16x32_bf16 v[64:67], v[152:155], v[184:187], v[64:67]
	v_mfma_f32_16x16x32_bf16 v[60:63], v[160:163], v[184:187], v[60:63]
	v_mfma_f32_16x16x32_bf16 v[48:51], v[152:155], v[192:195], v[48:51]
	v_mfma_f32_16x16x32_bf16 v[44:47], v[160:163], v[192:195], v[44:47]
	v_mfma_f32_16x16x32_bf16 v[32:35], v[152:155], v[200:203], v[32:35]
	v_mfma_f32_16x16x32_bf16 v[28:31], v[160:163], v[200:203], v[28:31]
	v_mfma_f32_16x16x32_bf16 v[16:19], v[152:155], v[230:233], v[16:19]
	v_mfma_f32_16x16x32_bf16 v[12:15], v[160:163], v[230:233], v[12:15]
	v_mfma_f32_16x16x32_bf16 v[64:67], v[156:159], v[188:191], v[64:67]
	v_mfma_f32_16x16x32_bf16 v[60:63], v[164:167], v[188:191], v[60:63]
	v_mfma_f32_16x16x32_bf16 v[48:51], v[156:159], v[196:199], v[48:51]
	v_mfma_f32_16x16x32_bf16 v[44:47], v[164:167], v[196:199], v[44:47]
	v_mfma_f32_16x16x32_bf16 v[32:35], v[156:159], v[204:207], v[32:35]
	v_mfma_f32_16x16x32_bf16 v[28:31], v[164:167], v[204:207], v[28:31]
	v_mfma_f32_16x16x32_bf16 v[16:19], v[156:159], v[240:243], v[16:19]
	v_mfma_f32_16x16x32_bf16 v[12:15], v[164:167], v[240:243], v[12:15]
	s_setprio 0
	s_setprio 1
	v_mfma_f32_16x16x32_bf16 v[56:59], v[168:171], v[184:187], v[56:59]
	v_mfma_f32_16x16x32_bf16 v[52:55], v[176:179], v[184:187], v[52:55]
	v_mfma_f32_16x16x32_bf16 v[40:43], v[168:171], v[192:195], v[40:43]
	v_mfma_f32_16x16x32_bf16 v[36:39], v[176:179], v[192:195], v[36:39]
	v_mfma_f32_16x16x32_bf16 v[24:27], v[168:171], v[200:203], v[24:27]
	v_mfma_f32_16x16x32_bf16 v[20:23], v[176:179], v[200:203], v[20:23]
	v_mfma_f32_16x16x32_bf16 v[8:11], v[168:171], v[230:233], v[8:11]
	v_mfma_f32_16x16x32_bf16 v[4:7], v[176:179], v[230:233], v[4:7]
	s_add_i32 s74, s74, 2
	s_add_u32 s4, s4, 0x100
	s_addc_u32 s5, s5, 0
	s_add_u32 s72, s72, 0x100
	s_addc_u32 s73, s73, 0
	s_cmp_gt_u32 s74, 13
	v_mfma_f32_16x16x32_bf16 v[56:59], v[172:175], v[188:191], v[56:59]
	v_mfma_f32_16x16x32_bf16 v[52:55], v[180:183], v[188:191], v[52:55]
	v_mfma_f32_16x16x32_bf16 v[40:43], v[172:175], v[196:199], v[40:43]
	v_mfma_f32_16x16x32_bf16 v[36:39], v[180:183], v[196:199], v[36:39]
	v_mfma_f32_16x16x32_bf16 v[24:27], v[172:175], v[204:207], v[24:27]
	v_mfma_f32_16x16x32_bf16 v[20:23], v[180:183], v[204:207], v[20:23]
	v_mfma_f32_16x16x32_bf16 v[8:11], v[172:175], v[240:243], v[8:11]
	v_mfma_f32_16x16x32_bf16 v[4:7], v[180:183], v[240:243], v[4:7]
	s_setprio 0
	s_barrier
	s_cbranch_scc0 .LBB0_1875
	s_and_b64 vcc, exec, s[22:23]
	s_cbranch_vccz .LBB0_1878
	s_barrier

.LBB0_2003:
	s_add_i32 s55, 0, 0x10000
	v_add_u32_e32 v157, s55, v155
	s_add_i32 s56, 0, 0x14000
	ds_read_b128 v[132:135], v157
	ds_read_b128 v[136:139], v157 offset:1024
	ds_read_b128 v[150:153], v157 offset:2048
	ds_read_b128 v[158:161], v157 offset:3072
	v_add_u32_e32 v157, s56, v155
	ds_read_b128 v[162:165], v157
	ds_read_b128 v[166:169], v157 offset:1024
	ds_read_b128 v[170:173], v157 offset:2048
	ds_read_b128 v[174:177], v157 offset:3072
	ds_read_b128 v[178:181], v156
	ds_read_b128 v[182:185], v156 offset:1024
	ds_read_b128 v[186:189], v156 offset:2048
	ds_read_b128 v[190:193], v156 offset:3072
	ds_read_b128 v[194:197], v156 offset:4096
	ds_read_b128 v[198:201], v156 offset:5120
	ds_read_b128 v[202:205], v156 offset:6144
	ds_read_b128 v[206:209], v156 offset:7168
	s_add_u32 s24, s6, 0x100
	s_addc_u32 s25, s7, 0
	s_cmp_eq_u32 s54, 40
	s_cselect_b32 s29, s21, s25
	s_cselect_b32 s28, s20, s24
	s_cselect_b32 s27, s23, s53
	s_cselect_b32 s26, s22, s52
	v_lshl_add_u64 v[230:231], s[6:7], 0, v[146:147]
	s_add_i32 m0, s40, 0xc000
	s_nop 0
	global_load_lds_dwordx4 v[230:231], off
	v_lshl_add_u64 v[230:231], s[6:7], 0, v[148:149]
	s_add_i32 m0, s40, 0xe000
	s_nop 0
	global_load_lds_dwordx4 v[230:231], off
	s_waitcnt vmcnt(8)
	s_waitcnt lgkmcnt(0)
	s_barrier
	s_setprio 1
	s_waitcnt lgkmcnt(0)
	v_mfma_f32_16x16x32_bf16 v[128:131], v[132:135], v[178:181], v[128:131]
	v_mfma_f32_16x16x32_bf16 v[124:127], v[150:153], v[178:181], v[124:127]
	v_mfma_f32_16x16x32_bf16 v[112:115], v[132:135], v[186:189], v[112:115]
	v_mfma_f32_16x16x32_bf16 v[108:111], v[150:153], v[186:189], v[108:111]
	v_mfma_f32_16x16x32_bf16 v[96:99], v[132:135], v[194:197], v[96:99]
	v_mfma_f32_16x16x32_bf16 v[92:95], v[150:153], v[194:197], v[92:95]
	v_mfma_f32_16x16x32_bf16 v[80:83], v[132:135], v[202:205], v[80:83]
	v_mfma_f32_16x16x32_bf16 v[76:79], v[150:153], v[202:205], v[76:79]
	v_mfma_f32_16x16x32_bf16 v[128:131], v[136:139], v[182:185], v[128:131]
	v_mfma_f32_16x16x32_bf16 v[124:127], v[158:161], v[182:185], v[124:127]
	v_mfma_f32_16x16x32_bf16 v[112:115], v[136:139], v[190:193], v[112:115]
	v_mfma_f32_16x16x32_bf16 v[108:111], v[158:161], v[190:193], v[108:111]
	v_mfma_f32_16x16x32_bf16 v[96:99], v[136:139], v[198:201], v[96:99]
	v_mfma_f32_16x16x32_bf16 v[92:95], v[158:161], v[198:201], v[92:95]
	v_mfma_f32_16x16x32_bf16 v[80:83], v[136:139], v[206:209], v[80:83]
	v_mfma_f32_16x16x32_bf16 v[76:79], v[158:161], v[206:209], v[76:79]
	s_setprio 0
	s_setprio 1
	v_mfma_f32_16x16x32_bf16 v[120:123], v[162:165], v[178:181], v[120:123]
	v_mfma_f32_16x16x32_bf16 v[116:119], v[170:173], v[178:181], v[116:119]
	v_mfma_f32_16x16x32_bf16 v[104:107], v[162:165], v[186:189], v[104:107]
	v_mfma_f32_16x16x32_bf16 v[100:103], v[170:173], v[186:189], v[100:103]
	v_mfma_f32_16x16x32_bf16 v[88:91], v[162:165], v[194:197], v[88:91]
	v_mfma_f32_16x16x32_bf16 v[84:87], v[170:173], v[194:197], v[84:87]
	v_mfma_f32_16x16x32_bf16 v[72:75], v[162:165], v[202:205], v[72:75]
	v_mfma_f32_16x16x32_bf16 v[68:71], v[170:173], v[202:205], v[68:71]
	v_mfma_f32_16x16x32_bf16 v[120:123], v[166:169], v[182:185], v[120:123]
	v_mfma_f32_16x16x32_bf16 v[116:119], v[174:177], v[182:185], v[116:119]
	v_mfma_f32_16x16x32_bf16 v[104:107], v[166:169], v[190:193], v[104:107]
	v_mfma_f32_16x16x32_bf16 v[100:103], v[174:177], v[190:193], v[100:103]
	v_mfma_f32_16x16x32_bf16 v[88:91], v[166:169], v[198:201], v[88:91]
	v_mfma_f32_16x16x32_bf16 v[84:87], v[174:177], v[198:201], v[84:87]
	v_mfma_f32_16x16x32_bf16 v[72:75], v[166:169], v[206:209], v[72:75]
	v_mfma_f32_16x16x32_bf16 v[68:71], v[174:177], v[206:209], v[68:71]
	s_setprio 0
	s_barrier
	ds_read_b128 v[178:181], v156 offset:16384
	ds_read_b128 v[182:185], v156 offset:17408
	ds_read_b128 v[186:189], v156 offset:18432
	ds_read_b128 v[190:193], v156 offset:19456
	ds_read_b128 v[194:197], v156 offset:20480
	ds_read_b128 v[198:201], v156 offset:21504
	ds_read_b128 v[202:205], v156 offset:22528
	ds_read_b128 v[206:209], v156 offset:23552
	s_add_i32 s6, s55, s39
	v_lshl_add_u64 v[230:231], s[26:27], 0, v[140:141]
	s_mov_b32 m0, s6
	s_nop 0
	global_load_lds_dwordx4 v[230:231], off
	s_add_i32 m0, s6, 0x2000
	s_add_u32 s6, s26, 0xb0000
	v_lshl_add_u64 v[232:233], s[26:27], 0, v[144:145]
	s_addc_u32 s7, s27, 0
	s_add_i32 s55, s56, s39
	global_load_lds_dwordx4 v[232:233], off
	v_lshl_add_u64 v[234:235], s[6:7], 0, v[140:141]
	s_mov_b32 m0, s55
	v_lshl_add_u64 v[240:241], s[28:29], 0, v[142:143]
	global_load_lds_dwordx4 v[234:235], off
	v_lshl_add_u64 v[234:235], s[6:7], 0, v[144:145]
	s_add_i32 m0, s55, 0x2000
	s_nop 0
	global_load_lds_dwordx4 v[234:235], off
	v_lshl_add_u64 v[234:235], s[28:29], 0, v[0:1]
	s_mov_b32 m0, s40
	s_nop 0
	global_load_lds_dwordx4 v[234:235], off
	s_mov_b32 m0, s41
	s_nop 0
	global_load_lds_dwordx4 v[240:241], off
	s_waitcnt vmcnt(8)
	s_waitcnt lgkmcnt(0)
	s_barrier
	s_setprio 1
	s_waitcnt lgkmcnt(0)
	v_mfma_f32_16x16x32_bf16 v[64:67], v[132:135], v[178:181], v[64:67]
	v_mfma_f32_16x16x32_bf16 v[60:63], v[150:153], v[178:181], v[60:63]
	v_mfma_f32_16x16x32_bf16 v[48:51], v[132:135], v[186:189], v[48:51]
	v_mfma_f32_16x16x32_bf16 v[44:47], v[150:153], v[186:189], v[44:47]
	v_mfma_f32_16x16x32_bf16 v[32:35], v[132:135], v[194:197], v[32:35]
	v_mfma_f32_16x16x32_bf16 v[28:31], v[150:153], v[194:197], v[28:31]
	v_mfma_f32_16x16x32_bf16 v[16:19], v[132:135], v[202:205], v[16:19]
	v_mfma_f32_16x16x32_bf16 v[12:15], v[150:153], v[202:205], v[12:15]
	v_mfma_f32_16x16x32_bf16 v[64:67], v[136:139], v[182:185], v[64:67]
	v_mfma_f32_16x16x32_bf16 v[60:63], v[158:161], v[182:185], v[60:63]
	v_mfma_f32_16x16x32_bf16 v[48:51], v[136:139], v[190:193], v[48:51]
	v_mfma_f32_16x16x32_bf16 v[44:47], v[158:161], v[190:193], v[44:47]
	v_mfma_f32_16x16x32_bf16 v[32:35], v[136:139], v[198:201], v[32:35]
	v_mfma_f32_16x16x32_bf16 v[28:31], v[158:161], v[198:201], v[28:31]
	v_mfma_f32_16x16x32_bf16 v[16:19], v[136:139], v[206:209], v[16:19]
	v_mfma_f32_16x16x32_bf16 v[12:15], v[158:161], v[206:209], v[12:15]
	s_setprio 0
	s_setprio 1
	v_mfma_f32_16x16x32_bf16 v[56:59], v[162:165], v[178:181], v[56:59]
	v_mfma_f32_16x16x32_bf16 v[52:55], v[170:173], v[178:181], v[52:55]
	v_mfma_f32_16x16x32_bf16 v[40:43], v[162:165], v[186:189], v[40:43]
	v_mfma_f32_16x16x32_bf16 v[36:39], v[170:173], v[186:189], v[36:39]
	v_mfma_f32_16x16x32_bf16 v[24:27], v[162:165], v[194:197], v[24:27]
	v_mfma_f32_16x16x32_bf16 v[20:23], v[170:173], v[194:197], v[20:23]
	v_mfma_f32_16x16x32_bf16 v[8:11], v[162:165], v[202:205], v[8:11]
	v_mfma_f32_16x16x32_bf16 v[4:7], v[170:173], v[202:205], v[4:7]
	v_mfma_f32_16x16x32_bf16 v[56:59], v[166:169], v[182:185], v[56:59]
	v_mfma_f32_16x16x32_bf16 v[52:55], v[174:177], v[182:185], v[52:55]
	v_mfma_f32_16x16x32_bf16 v[40:43], v[166:169], v[190:193], v[40:43]
	v_mfma_f32_16x16x32_bf16 v[36:39], v[174:177], v[190:193], v[36:39]
	v_mfma_f32_16x16x32_bf16 v[24:27], v[166:169], v[198:201], v[24:27]
	v_mfma_f32_16x16x32_bf16 v[20:23], v[174:177], v[198:201], v[20:23]
	v_mfma_f32_16x16x32_bf16 v[8:11], v[166:169], v[206:209], v[8:11]
	v_mfma_f32_16x16x32_bf16 v[4:7], v[174:177], v[206:209], v[4:7]
	s_setprio 0
	s_barrier
	s_add_i32 s55, 0, 0x18000
	v_add_u32_e32 v157, s55, v155
	s_add_i32 s56, 0, 0x1c000
	ds_read_b128 v[132:135], v157
	ds_read_b128 v[136:139], v157 offset:1024
	ds_read_b128 v[150:153], v157 offset:2048
	ds_read_b128 v[158:161], v157 offset:3072
	v_add_u32_e32 v157, s56, v155
	ds_read_b128 v[162:165], v157
	ds_read_b128 v[166:169], v157 offset:1024
	ds_read_b128 v[170:173], v157 offset:2048
	ds_read_b128 v[174:177], v157 offset:3072
	ds_read_b128 v[178:181], v156 offset:32768
	ds_read_b128 v[182:185], v156 offset:33792
	ds_read_b128 v[186:189], v156 offset:34816
	ds_read_b128 v[190:193], v156 offset:35840
	ds_read_b128 v[194:197], v156 offset:36864
	ds_read_b128 v[198:201], v156 offset:37888
	ds_read_b128 v[202:205], v156 offset:38912
	ds_read_b128 v[206:209], v156 offset:39936
	s_add_u32 s6, s28, 0xb0000
	s_addc_u32 s7, s29, 0
	s_mov_b32 m0, s42
	v_lshl_add_u64 v[242:243], s[6:7], 0, v[0:1]
	global_load_lds_dwordx4 v[242:243], off
	v_lshl_add_u64 v[242:243], s[6:7], 0, v[142:143]
	s_mov_b32 m0, s43
	s_nop 0
	global_load_lds_dwordx4 v[242:243], off
	s_waitcnt vmcnt(8)
	s_waitcnt lgkmcnt(0)
	s_barrier
	s_setprio 1
	s_waitcnt lgkmcnt(0)
	v_mfma_f32_16x16x32_bf16 v[128:131], v[132:135], v[178:181], v[128:131]
	v_mfma_f32_16x16x32_bf16 v[124:127], v[150:153], v[178:181], v[124:127]
	v_mfma_f32_16x16x32_bf16 v[112:115], v[132:135], v[186:189], v[112:115]
	v_mfma_f32_16x16x32_bf16 v[108:111], v[150:153], v[186:189], v[108:111]
	v_mfma_f32_16x16x32_bf16 v[96:99], v[132:135], v[194:197], v[96:99]
	v_mfma_f32_16x16x32_bf16 v[92:95], v[150:153], v[194:197], v[92:95]
	v_mfma_f32_16x16x32_bf16 v[80:83], v[132:135], v[202:205], v[80:83]
	v_mfma_f32_16x16x32_bf16 v[76:79], v[150:153], v[202:205], v[76:79]
	v_mfma_f32_16x16x32_bf16 v[128:131], v[136:139], v[182:185], v[128:131]
	v_mfma_f32_16x16x32_bf16 v[124:127], v[158:161], v[182:185], v[124:127]
	v_mfma_f32_16x16x32_bf16 v[112:115], v[136:139], v[190:193], v[112:115]
	v_mfma_f32_16x16x32_bf16 v[108:111], v[158:161], v[190:193], v[108:111]
	v_mfma_f32_16x16x32_bf16 v[96:99], v[136:139], v[198:201], v[96:99]
	v_mfma_f32_16x16x32_bf16 v[92:95], v[158:161], v[198:201], v[92:95]
	v_mfma_f32_16x16x32_bf16 v[80:83], v[136:139], v[206:209], v[80:83]
	v_mfma_f32_16x16x32_bf16 v[76:79], v[158:161], v[206:209], v[76:79]
	s_setprio 0
	s_setprio 1
	v_mfma_f32_16x16x32_bf16 v[120:123], v[162:165], v[178:181], v[120:123]
	v_mfma_f32_16x16x32_bf16 v[116:119], v[170:173], v[178:181], v[116:119]
	v_mfma_f32_16x16x32_bf16 v[104:107], v[162:165], v[186:189], v[104:107]
	v_mfma_f32_16x16x32_bf16 v[100:103], v[170:173], v[186:189], v[100:103]
	v_mfma_f32_16x16x32_bf16 v[88:91], v[162:165], v[194:197], v[88:91]
	v_mfma_f32_16x16x32_bf16 v[84:87], v[170:173], v[194:197], v[84:87]
	v_mfma_f32_16x16x32_bf16 v[72:75], v[162:165], v[202:205], v[72:75]
	v_mfma_f32_16x16x32_bf16 v[68:71], v[170:173], v[202:205], v[68:71]
	v_mfma_f32_16x16x32_bf16 v[120:123], v[166:169], v[182:185], v[120:123]
	v_mfma_f32_16x16x32_bf16 v[116:119], v[174:177], v[182:185], v[116:119]
	v_mfma_f32_16x16x32_bf16 v[104:107], v[166:169], v[190:193], v[104:107]
	v_mfma_f32_16x16x32_bf16 v[100:103], v[174:177], v[190:193], v[100:103]
	v_mfma_f32_16x16x32_bf16 v[88:91], v[166:169], v[198:201], v[88:91]
	v_mfma_f32_16x16x32_bf16 v[84:87], v[174:177], v[198:201], v[84:87]
	v_mfma_f32_16x16x32_bf16 v[72:75], v[166:169], v[206:209], v[72:75]
	v_mfma_f32_16x16x32_bf16 v[68:71], v[174:177], v[206:209], v[68:71]
	s_setprio 0
	s_barrier
	ds_read_b128 v[178:181], v156 offset:49152
	ds_read_b128 v[182:185], v156 offset:50176
	ds_read_b128 v[186:189], v156 offset:51200
	ds_read_b128 v[190:193], v156 offset:52224
	ds_read_b128 v[194:197], v156 offset:53248
	ds_read_b128 v[198:201], v156 offset:54272
	ds_read_b128 v[202:205], v156 offset:55296
	ds_read_b128 v[206:209], v156 offset:56320
	s_add_i32 s6, s55, s39
	v_lshl_add_u64 v[230:231], v[230:231], 0, s[58:59]
	s_mov_b32 m0, s6
	s_nop 0
	global_load_lds_dwordx4 v[230:231], off
	s_add_i32 m0, s6, 0x2000
	s_add_u32 s6, s26, 0xb0080
	v_lshl_add_u64 v[230:231], v[232:233], 0, s[58:59]
	s_addc_u32 s7, s27, 0
	s_add_i32 s26, s56, s39
	global_load_lds_dwordx4 v[230:231], off
	v_lshl_add_u64 v[230:231], s[6:7], 0, v[140:141]
	s_mov_b32 m0, s26
	s_nop 0
	global_load_lds_dwordx4 v[230:231], off
	v_lshl_add_u64 v[230:231], s[6:7], 0, v[144:145]
	s_add_i32 m0, s26, 0x2000
	s_nop 0
	global_load_lds_dwordx4 v[230:231], off
	v_lshl_add_u64 v[230:231], v[234:235], 0, s[58:59]
	s_mov_b32 m0, s45
	s_nop 0
	global_load_lds_dwordx4 v[230:231], off
	v_lshl_add_u64 v[230:231], v[240:241], 0, s[58:59]
	s_mov_b32 m0, s46
	s_nop 0
	global_load_lds_dwordx4 v[230:231], off
	s_waitcnt vmcnt(8)
	s_waitcnt lgkmcnt(0)
	s_barrier
	s_setprio 1
	s_waitcnt lgkmcnt(0)
	v_mfma_f32_16x16x32_bf16 v[64:67], v[132:135], v[178:181], v[64:67]
	v_mfma_f32_16x16x32_bf16 v[60:63], v[150:153], v[178:181], v[60:63]
	v_mfma_f32_16x16x32_bf16 v[48:51], v[132:135], v[186:189], v[48:51]
	v_mfma_f32_16x16x32_bf16 v[44:47], v[150:153], v[186:189], v[44:47]
	v_mfma_f32_16x16x32_bf16 v[32:35], v[132:135], v[194:197], v[32:35]
	v_mfma_f32_16x16x32_bf16 v[28:31], v[150:153], v[194:197], v[28:31]
	v_mfma_f32_16x16x32_bf16 v[16:19], v[132:135], v[202:205], v[16:19]
	v_mfma_f32_16x16x32_bf16 v[12:15], v[150:153], v[202:205], v[12:15]
	v_mfma_f32_16x16x32_bf16 v[64:67], v[136:139], v[182:185], v[64:67]
	v_mfma_f32_16x16x32_bf16 v[60:63], v[158:161], v[182:185], v[60:63]
	v_mfma_f32_16x16x32_bf16 v[48:51], v[136:139], v[190:193], v[48:51]
	v_mfma_f32_16x16x32_bf16 v[44:47], v[158:161], v[190:193], v[44:47]
	v_mfma_f32_16x16x32_bf16 v[32:35], v[136:139], v[198:201], v[32:35]
	v_mfma_f32_16x16x32_bf16 v[28:31], v[158:161], v[198:201], v[28:31]
	v_mfma_f32_16x16x32_bf16 v[16:19], v[136:139], v[206:209], v[16:19]
	v_mfma_f32_16x16x32_bf16 v[12:15], v[158:161], v[206:209], v[12:15]
	s_setprio 0
	s_setprio 1
	v_mfma_f32_16x16x32_bf16 v[56:59], v[162:165], v[178:181], v[56:59]
	v_mfma_f32_16x16x32_bf16 v[52:55], v[170:173], v[178:181], v[52:55]
	v_mfma_f32_16x16x32_bf16 v[40:43], v[162:165], v[186:189], v[40:43]
	v_mfma_f32_16x16x32_bf16 v[36:39], v[170:173], v[186:189], v[36:39]
	v_mfma_f32_16x16x32_bf16 v[24:27], v[162:165], v[194:197], v[24:27]
	v_mfma_f32_16x16x32_bf16 v[20:23], v[170:173], v[194:197], v[20:23]
	v_mfma_f32_16x16x32_bf16 v[8:11], v[162:165], v[202:205], v[8:11]
	v_mfma_f32_16x16x32_bf16 v[4:7], v[170:173], v[202:205], v[4:7]
	s_add_i32 s54, s54, 2
	s_add_u32 s52, s52, 0x100
	s_addc_u32 s53, s53, 0
	s_cmp_gt_u32 s54, 41
	s_mov_b64 s[6:7], s[24:25]
	v_mfma_f32_16x16x32_bf16 v[56:59], v[166:169], v[182:185], v[56:59]
	v_mfma_f32_16x16x32_bf16 v[52:55], v[174:177], v[182:185], v[52:55]
	v_mfma_f32_16x16x32_bf16 v[40:43], v[166:169], v[190:193], v[40:43]
	v_mfma_f32_16x16x32_bf16 v[36:39], v[174:177], v[190:193], v[36:39]
	v_mfma_f32_16x16x32_bf16 v[24:27], v[166:169], v[198:201], v[24:27]
	v_mfma_f32_16x16x32_bf16 v[20:23], v[174:177], v[198:201], v[20:23]
	v_mfma_f32_16x16x32_bf16 v[8:11], v[166:169], v[206:209], v[8:11]
	v_mfma_f32_16x16x32_bf16 v[4:7], v[174:177], v[206:209], v[4:7]
	s_setprio 0
	s_barrier
	s_cbranch_scc0 .LBB0_2003
	s_and_b64 vcc, exec, s[18:19]
	s_cbranch_vccz .LBB0_2006
	s_barrier
